# v11s: as v11 with snake MFMA pair order (n0: m0..m3, n1: m3..m0)
# speedup vs baseline: 1.0105x; 1.0049x over previous
; #define PG8_STAGE(bufoff, gbase, voff) do { _Pragma("unroll") for (int _i = 0; _i < 2; ++_i) \
;         __builtin_amdgcn_global_load_lds((const unsigned*)((const char*)(gbase) + (voff)[_i]), (PG8_LAS unsigned*)(lds + (bufoff) + ldsw + _i * 8192), 16, 0, 0); } while (0)
; #define PG8_LDA(dst, b, h) do { _Pragma("unroll") for (int m = 0; m < 4; ++m) _Pragma("unroll") for (int k = 0; k < 2; ++k) dst[m][k] = *(const PG8_LAS bf16x8*)(lds + PG8_SA(b, h) + aoff + m * 2048 + k * 1024); } while (0)
; #define PG8_LDB(dst, b, h) do { _Pragma("unroll") for (int n = 0; n < 2; ++n) _Pragma("unroll") for (int k = 0; k < 2; ++k) dst[n][k] = *(const PG8_LAS bf16x8*)(lds + PG8_SB(b, h) + boff + n * 2048 + k * 1024); } while (0)
; #define PG8_MMA(ai, bj, At, Bt) do { __builtin_amdgcn_s_setprio(1); _Pragma("unroll") for (int m = 0; m < 4; ++m) _Pragma("unroll") for (int n = 0; n < 2; ++n) _Pragma("unroll") for (int k = 0; k < 2; ++k) \
;         acc[ai][bj][m][n] = __builtin_amdgcn_mfma_f32_16x16x32_bf16(Bt[n][k], At[m][k], acc[ai][bj][m][n], 0, 0, 0); __builtin_amdgcn_s_setprio(0); } while (0)
; #define PG8_WAIT_V(n) asm volatile("s_waitcnt vmcnt(" #n ")" ::: "memory")
; #define PG8_WAIT_L(n) asm volatile("s_waitcnt lgkmcnt(" #n ")" ::: "memory")
; template <class Epi, class Sched, bool ALIGN_EPI = false, bool SP2 = false>
; __device__ __forceinline__ void gemm_phase(PG8_LAS unsigned char* lds, const Gemm g, const Sched& S, const Epi& E) {
;     ...
;             const bool last = (t == nt - 2);
;             const char* a1 = cA + (size_t)(t + 1) * kstep;
;             const char* a2 = last ? nA : cA + (size_t)(t + 2) * kstep; const char* b2 = last ? nB : cB + (size_t)(t + 2) * kstep;
;             const char* a3 = a2 + kstep; const char* b3 = b2 + kstep;
;             if (last && has_next) S.a_ready(nxt);
;             if constexpr (SP2) {
;             PG8_LDB(B0, 0, 0); PG8_LDB(B1, 0, 1); PG8_SCHED; PG8_LDA(At, 0, 0); PG8_STAGE(PG8_SA(1, 1), a1 + hstep, voffA);
;             PG8_WAIT_V(8); PG8_WAIT_L(0); PG8_BAR; PG8_MMA(0, 0, At, B0); PG8_MMA(0, 1, At, B1); PG8_BAR; PG8_SCHED;
;             PG8_LDA(At, 0, 1); PG8_STAGE(PG8_SB(0, 0), b2, voffB); PG8_STAGE(PG8_SB(0, 1), b2 + hstep, voffB); PG8_STAGE(PG8_SA(0, 0), a2, voffA);
;             PG8_WAIT_V(8); PG8_WAIT_L(0); PG8_BAR; PG8_MMA(1, 0, At, B0); PG8_MMA(1, 1, At, B1); PG8_BAR; PG8_SCHED;
.LBB0_115:
	ds_read_b128 v[154:157], v150
	ds_read_b128 v[158:161], v150 offset:1024
	ds_read_b128 v[162:165], v150 offset:2048
	ds_read_b128 v[166:169], v150 offset:3072
	ds_read_b128 v[170:173], v151
	ds_read_b128 v[174:177], v151 offset:1024
	ds_read_b128 v[180:183], v151 offset:2048
	ds_read_b128 v[184:187], v151 offset:3072
	s_add_u32 s50, s48, 0x4000
	s_addc_u32 s51, s49, 0
	s_cmp_eq_u32 s76, 60
	s_cselect_b32 s74, s64, s50
	s_cselect_b32 s75, s25, s51
	s_cselect_b32 s72, s65, s68
	s_cselect_b32 s73, s19, s69
	s_add_u32 s50, s74, 0x8000
	s_addc_u32 s51, s75, 0
	s_sub_u32 s50, s48, 0x4000
	s_subb_u32 s51, s49, 0
	s_mov_b32 m0, s58
	s_nop 0
	global_load_lds_dwordx4 v130, s[50:51]
	s_mov_b32 m0, s59
	s_nop 0
	global_load_lds_dwordx4 v134, s[50:51]
	s_add_i32 m0, s28, 0xc000
	ds_read_b128 v[188:191], v152
	ds_read_b128 v[196:199], v152 offset:1024
	ds_read_b128 v[200:203], v152 offset:2048
	ds_read_b128 v[204:207], v152 offset:3072
	ds_read_b128 v[208:211], v152 offset:4096
	ds_read_b128 v[212:215], v152 offset:5120
	ds_read_b128 v[216:219], v152 offset:6144
	ds_read_b128 v[220:223], v152 offset:7168
	global_load_lds_dwordx4 v140, s[48:49]
	s_add_i32 m0, s28, 0xe000
	s_nop 0
	global_load_lds_dwordx4 v142, s[48:49]
	s_waitcnt vmcnt(8)
	s_waitcnt lgkmcnt(0)
	s_barrier
	s_setprio 1
	s_waitcnt lgkmcnt(0)
	v_mfma_f32_16x16x32_bf16 v[126:129], v[154:157], v[188:191], v[126:129]
	v_mfma_f32_16x16x32_bf16 v[126:129], v[158:161], v[196:199], v[126:129]
	v_mfma_f32_16x16x32_bf16 v[110:113], v[154:157], v[200:203], v[110:113]
	v_mfma_f32_16x16x32_bf16 v[110:113], v[158:161], v[204:207], v[110:113]
	v_mfma_f32_16x16x32_bf16 v[94:97], v[154:157], v[208:211], v[94:97]
	v_mfma_f32_16x16x32_bf16 v[94:97], v[158:161], v[212:215], v[94:97]
	v_mfma_f32_16x16x32_bf16 v[78:81], v[154:157], v[216:219], v[78:81]
	v_mfma_f32_16x16x32_bf16 v[78:81], v[158:161], v[220:223], v[78:81]
	v_mfma_f32_16x16x32_bf16 v[70:73], v[162:165], v[216:219], v[70:73]
	v_mfma_f32_16x16x32_bf16 v[70:73], v[166:169], v[220:223], v[70:73]
	v_mfma_f32_16x16x32_bf16 v[86:89], v[162:165], v[208:211], v[86:89]
	v_mfma_f32_16x16x32_bf16 v[86:89], v[166:169], v[212:215], v[86:89]
	v_mfma_f32_16x16x32_bf16 v[102:105], v[162:165], v[200:203], v[102:105]
	v_mfma_f32_16x16x32_bf16 v[102:105], v[166:169], v[204:207], v[102:105]
	v_mfma_f32_16x16x32_bf16 v[118:121], v[162:165], v[188:191], v[118:121]
	v_mfma_f32_16x16x32_bf16 v[118:121], v[166:169], v[196:199], v[118:121]
	s_setprio 0
	s_setprio 1
	v_mfma_f32_16x16x32_bf16 v[122:125], v[170:173], v[188:191], v[122:125]
	v_mfma_f32_16x16x32_bf16 v[122:125], v[174:177], v[196:199], v[122:125]
	v_mfma_f32_16x16x32_bf16 v[106:109], v[170:173], v[200:203], v[106:109]
	v_mfma_f32_16x16x32_bf16 v[106:109], v[174:177], v[204:207], v[106:109]
	v_mfma_f32_16x16x32_bf16 v[90:93], v[170:173], v[208:211], v[90:93]
	v_mfma_f32_16x16x32_bf16 v[90:93], v[174:177], v[212:215], v[90:93]
	v_mfma_f32_16x16x32_bf16 v[74:77], v[170:173], v[216:219], v[74:77]
	v_mfma_f32_16x16x32_bf16 v[74:77], v[174:177], v[220:223], v[74:77]
	v_mfma_f32_16x16x32_bf16 v[66:69], v[180:183], v[216:219], v[66:69]
	v_mfma_f32_16x16x32_bf16 v[66:69], v[184:187], v[220:223], v[66:69]
	v_mfma_f32_16x16x32_bf16 v[82:85], v[180:183], v[208:211], v[82:85]
	v_mfma_f32_16x16x32_bf16 v[82:85], v[184:187], v[212:215], v[82:85]
	v_mfma_f32_16x16x32_bf16 v[98:101], v[180:183], v[200:203], v[98:101]
	v_mfma_f32_16x16x32_bf16 v[98:101], v[184:187], v[204:207], v[98:101]
	v_mfma_f32_16x16x32_bf16 v[114:117], v[180:183], v[188:191], v[114:117]
	v_mfma_f32_16x16x32_bf16 v[114:117], v[184:187], v[196:199], v[114:117]
	s_setprio 0
	s_barrier
	s_add_i32 s77, s61, s3
	s_mov_b32 m0, s77
	ds_read_b128 v[188:191], v152 offset:16384
	ds_read_b128 v[196:199], v152 offset:17408
	ds_read_b128 v[200:203], v152 offset:18432
	ds_read_b128 v[204:207], v152 offset:19456
	ds_read_b128 v[208:211], v152 offset:20480
	ds_read_b128 v[212:215], v152 offset:21504
	ds_read_b128 v[216:219], v152 offset:22528
	ds_read_b128 v[220:223], v152 offset:23552
	global_load_lds_dwordx4 v132, s[72:73]
	s_add_i32 m0, s77, 0x2000
	s_add_u32 s78, s72, 0x4000
	v_lshl_add_u64 v[224:225], s[72:73], 0, v[136:137]
	s_addc_u32 s79, s73, 0
	s_add_i32 s77, s62, s3
	global_load_lds_dwordx4 v[224:225], off
	s_mov_b32 m0, s77
	s_nop 0
	global_load_lds_dwordx4 v132, s[78:79]
	s_add_i32 m0, s77, 0x2000
	s_nop 0
	global_load_lds_dwordx4 v136, s[78:79]
	s_waitcnt vmcnt(6)
	s_waitcnt lgkmcnt(0)
	s_barrier
	s_setprio 1
	s_waitcnt lgkmcnt(0)
	v_mfma_f32_16x16x32_bf16 v[62:65], v[154:157], v[188:191], v[62:65]
	v_mfma_f32_16x16x32_bf16 v[62:65], v[158:161], v[196:199], v[62:65]
	v_mfma_f32_16x16x32_bf16 v[46:49], v[154:157], v[200:203], v[46:49]
	v_mfma_f32_16x16x32_bf16 v[46:49], v[158:161], v[204:207], v[46:49]
	v_mfma_f32_16x16x32_bf16 v[30:33], v[154:157], v[208:211], v[30:33]
	v_mfma_f32_16x16x32_bf16 v[30:33], v[158:161], v[212:215], v[30:33]
	v_mfma_f32_16x16x32_bf16 v[14:17], v[154:157], v[216:219], v[14:17]
	v_mfma_f32_16x16x32_bf16 v[14:17], v[158:161], v[220:223], v[14:17]
	v_mfma_f32_16x16x32_bf16 v[6:9], v[162:165], v[216:219], v[6:9]
	v_mfma_f32_16x16x32_bf16 v[6:9], v[166:169], v[220:223], v[6:9]
	v_mfma_f32_16x16x32_bf16 v[22:25], v[162:165], v[208:211], v[22:25]
	v_mfma_f32_16x16x32_bf16 v[22:25], v[166:169], v[212:215], v[22:25]
	v_mfma_f32_16x16x32_bf16 v[38:41], v[162:165], v[200:203], v[38:41]
	v_mfma_f32_16x16x32_bf16 v[38:41], v[166:169], v[204:207], v[38:41]
	v_mfma_f32_16x16x32_bf16 v[54:57], v[162:165], v[188:191], v[54:57]
	v_mfma_f32_16x16x32_bf16 v[54:57], v[166:169], v[196:199], v[54:57]
	s_setprio 0
	s_setprio 1
	v_mfma_f32_16x16x32_bf16 v[58:61], v[170:173], v[188:191], v[58:61]
	v_mfma_f32_16x16x32_bf16 v[58:61], v[174:177], v[196:199], v[58:61]
	v_mfma_f32_16x16x32_bf16 v[42:45], v[170:173], v[200:203], v[42:45]
	v_mfma_f32_16x16x32_bf16 v[42:45], v[174:177], v[204:207], v[42:45]
	v_mfma_f32_16x16x32_bf16 v[26:29], v[170:173], v[208:211], v[26:29]
	v_mfma_f32_16x16x32_bf16 v[26:29], v[174:177], v[212:215], v[26:29]
	v_mfma_f32_16x16x32_bf16 v[10:13], v[170:173], v[216:219], v[10:13]
	v_mfma_f32_16x16x32_bf16 v[10:13], v[174:177], v[220:223], v[10:13]
	v_mfma_f32_16x16x32_bf16 v[2:5], v[180:183], v[216:219], v[2:5]
	v_mfma_f32_16x16x32_bf16 v[2:5], v[184:187], v[220:223], v[2:5]
	v_mfma_f32_16x16x32_bf16 v[18:21], v[180:183], v[208:211], v[18:21]
	v_mfma_f32_16x16x32_bf16 v[18:21], v[184:187], v[212:215], v[18:21]
	v_mfma_f32_16x16x32_bf16 v[34:37], v[180:183], v[200:203], v[34:37]
	v_mfma_f32_16x16x32_bf16 v[34:37], v[184:187], v[204:207], v[34:37]
	v_mfma_f32_16x16x32_bf16 v[50:53], v[180:183], v[188:191], v[50:53]
	v_mfma_f32_16x16x32_bf16 v[50:53], v[184:187], v[196:199], v[50:53]
	s_setprio 0
	s_barrier
; #define PG8_STAGE(bufoff, gbase, voff) do { _Pragma("unroll") for (int _i = 0; _i < 2; ++_i) \
;         __builtin_amdgcn_global_load_lds((const unsigned*)((const char*)(gbase) + (voff)[_i]), (PG8_LAS unsigned*)(lds + (bufoff) + ldsw + _i * 8192), 16, 0, 0); } while (0)
; #define PG8_LDA(dst, b, h) do { _Pragma("unroll") for (int m = 0; m < 4; ++m) _Pragma("unroll") for (int k = 0; k < 2; ++k) dst[m][k] = *(const PG8_LAS bf16x8*)(lds + PG8_SA(b, h) + aoff + m * 2048 + k * 1024); } while (0)
; #define PG8_LDB(dst, b, h) do { _Pragma("unroll") for (int n = 0; n < 2; ++n) _Pragma("unroll") for (int k = 0; k < 2; ++k) dst[n][k] = *(const PG8_LAS bf16x8*)(lds + PG8_SB(b, h) + boff + n * 2048 + k * 1024); } while (0)
; #define PG8_MMA(ai, bj, At, Bt) do { __builtin_amdgcn_s_setprio(1); _Pragma("unroll") for (int m = 0; m < 4; ++m) _Pragma("unroll") for (int n = 0; n < 2; ++n) _Pragma("unroll") for (int k = 0; k < 2; ++k) \
;         acc[ai][bj][m][n] = __builtin_amdgcn_mfma_f32_16x16x32_bf16(Bt[n][k], At[m][k], acc[ai][bj][m][n], 0, 0, 0); __builtin_amdgcn_s_setprio(0); } while (0)
; #define PG8_WAIT_V(n) asm volatile("s_waitcnt vmcnt(" #n ")" ::: "memory")
; #define PG8_WAIT_L(n) asm volatile("s_waitcnt lgkmcnt(" #n ")" ::: "memory")
; #define PG8_BAR __builtin_amdgcn_s_barrier()
; #define PG8_SCHED __builtin_amdgcn_sched_barrier(0)
; template <class Epi, class Sched, bool ALIGN_EPI = false, bool SP2 = false>
; __device__ __forceinline__ void gemm_phase(PG8_LAS unsigned char* lds, const Gemm g, const Sched& S, const Epi& E) {
;     ...
;         for (; t < tend; t += 2) {
;     ...
;             PG8_LDB(B0, 1, 0); PG8_LDB(B1, 1, 1); PG8_SCHED; PG8_LDA(At, 1, 0); PG8_STAGE(PG8_SA(0, 1), a2 + hstep, voffA);
;             PG8_WAIT_V(8); PG8_WAIT_L(0); PG8_BAR; PG8_MMA(0, 0, At, B0); PG8_MMA(0, 1, At, B1); PG8_BAR; PG8_SCHED;
;             PG8_LDA(At, 1, 1); PG8_STAGE(PG8_SB(1, 0), b3, voffB); PG8_STAGE(PG8_SB(1, 1), b3 + hstep, voffB); PG8_STAGE(PG8_SA(1, 0), a3, voffA);
;             PG8_WAIT_V(8); PG8_WAIT_L(0); PG8_BAR; PG8_MMA(1, 0, At, B0); PG8_MMA(1, 1, At, B1); PG8_BAR; PG8_SCHED;
	s_add_i32 s77, 0, 0x18000
	v_add_u32_e32 v138, s77, v148
	s_add_i32 s78, 0, 0x1c000
	ds_read_b128 v[154:157], v138
	ds_read_b128 v[158:161], v138 offset:1024
	ds_read_b128 v[162:165], v138 offset:2048
	ds_read_b128 v[166:169], v138 offset:3072
	v_add_u32_e32 v138, s78, v148
	ds_read_b128 v[170:173], v138
	ds_read_b128 v[174:177], v138 offset:1024
	ds_read_b128 v[180:183], v138 offset:2048
	ds_read_b128 v[184:187], v138 offset:3072
	s_mov_b32 m0, s28
	s_nop 0
	global_load_lds_dwordx4 v130, s[74:75]
	s_mov_b32 m0, s29
	s_nop 0
	global_load_lds_dwordx4 v134, s[74:75]
	s_add_u32 s74, s74, 0x4000
	s_addc_u32 s75, s75, 0
	s_mov_b32 m0, s30
	ds_read_b128 v[188:191], v152 offset:32768
	ds_read_b128 v[196:199], v152 offset:33792
	ds_read_b128 v[200:203], v152 offset:34816
	ds_read_b128 v[204:207], v152 offset:35840
	ds_read_b128 v[208:211], v152 offset:36864
	ds_read_b128 v[212:215], v152 offset:37888
	ds_read_b128 v[216:219], v152 offset:38912
	ds_read_b128 v[220:223], v152 offset:39936
	global_load_lds_dwordx4 v130, s[74:75]
	s_mov_b32 m0, s31
	s_nop 0
	global_load_lds_dwordx4 v134, s[74:75]
	s_waitcnt vmcnt(8)
	s_waitcnt lgkmcnt(0)
	s_barrier
	s_setprio 1
	s_waitcnt lgkmcnt(0)
	v_mfma_f32_16x16x32_bf16 v[126:129], v[154:157], v[188:191], v[126:129]
	v_mfma_f32_16x16x32_bf16 v[126:129], v[158:161], v[196:199], v[126:129]
	v_mfma_f32_16x16x32_bf16 v[110:113], v[154:157], v[200:203], v[110:113]
	v_mfma_f32_16x16x32_bf16 v[110:113], v[158:161], v[204:207], v[110:113]
	v_mfma_f32_16x16x32_bf16 v[94:97], v[154:157], v[208:211], v[94:97]
	v_mfma_f32_16x16x32_bf16 v[94:97], v[158:161], v[212:215], v[94:97]
	v_mfma_f32_16x16x32_bf16 v[78:81], v[154:157], v[216:219], v[78:81]
	v_mfma_f32_16x16x32_bf16 v[78:81], v[158:161], v[220:223], v[78:81]
	v_mfma_f32_16x16x32_bf16 v[70:73], v[162:165], v[216:219], v[70:73]
	v_mfma_f32_16x16x32_bf16 v[70:73], v[166:169], v[220:223], v[70:73]
	v_mfma_f32_16x16x32_bf16 v[86:89], v[162:165], v[208:211], v[86:89]
	v_mfma_f32_16x16x32_bf16 v[86:89], v[166:169], v[212:215], v[86:89]
	v_mfma_f32_16x16x32_bf16 v[102:105], v[162:165], v[200:203], v[102:105]
	v_mfma_f32_16x16x32_bf16 v[102:105], v[166:169], v[204:207], v[102:105]
	v_mfma_f32_16x16x32_bf16 v[118:121], v[162:165], v[188:191], v[118:121]
	v_mfma_f32_16x16x32_bf16 v[118:121], v[166:169], v[196:199], v[118:121]
	s_setprio 0
	s_setprio 1
	v_mfma_f32_16x16x32_bf16 v[122:125], v[170:173], v[188:191], v[122:125]
	v_mfma_f32_16x16x32_bf16 v[122:125], v[174:177], v[196:199], v[122:125]
	v_mfma_f32_16x16x32_bf16 v[106:109], v[170:173], v[200:203], v[106:109]
	v_mfma_f32_16x16x32_bf16 v[106:109], v[174:177], v[204:207], v[106:109]
	v_mfma_f32_16x16x32_bf16 v[90:93], v[170:173], v[208:211], v[90:93]
	v_mfma_f32_16x16x32_bf16 v[90:93], v[174:177], v[212:215], v[90:93]
	v_mfma_f32_16x16x32_bf16 v[74:77], v[170:173], v[216:219], v[74:77]
	v_mfma_f32_16x16x32_bf16 v[74:77], v[174:177], v[220:223], v[74:77]
	v_mfma_f32_16x16x32_bf16 v[66:69], v[180:183], v[216:219], v[66:69]
	v_mfma_f32_16x16x32_bf16 v[66:69], v[184:187], v[220:223], v[66:69]
	v_mfma_f32_16x16x32_bf16 v[82:85], v[180:183], v[208:211], v[82:85]
	v_mfma_f32_16x16x32_bf16 v[82:85], v[184:187], v[212:215], v[82:85]
	v_mfma_f32_16x16x32_bf16 v[98:101], v[180:183], v[200:203], v[98:101]
	v_mfma_f32_16x16x32_bf16 v[98:101], v[184:187], v[204:207], v[98:101]
	v_mfma_f32_16x16x32_bf16 v[114:117], v[180:183], v[188:191], v[114:117]
	v_mfma_f32_16x16x32_bf16 v[114:117], v[184:187], v[196:199], v[114:117]
	s_setprio 0
	s_barrier
	s_add_u32 s74, s72, 0x8000
	s_addc_u32 s75, s73, 0
	s_add_i32 s77, s77, s3
	s_mov_b32 m0, s77
	ds_read_b128 v[188:191], v152 offset:49152
	ds_read_b128 v[196:199], v152 offset:50176
	ds_read_b128 v[200:203], v152 offset:51200
	ds_read_b128 v[204:207], v152 offset:52224
	ds_read_b128 v[208:211], v152 offset:53248
	ds_read_b128 v[212:215], v152 offset:54272
	ds_read_b128 v[216:219], v152 offset:55296
	ds_read_b128 v[220:223], v152 offset:56320
	global_load_lds_dwordx4 v132, s[74:75]
	s_add_i32 m0, s77, 0x2000
	s_add_u32 s72, s72, 0xc000
	v_lshl_add_u64 v[224:225], s[74:75], 0, v[136:137]
	s_addc_u32 s73, s73, 0
	s_add_i32 s74, s78, s3
	global_load_lds_dwordx4 v[224:225], off
	s_mov_b32 m0, s74
	s_nop 0
	global_load_lds_dwordx4 v132, s[72:73]
	s_add_i32 m0, s74, 0x2000
	s_nop 0
	global_load_lds_dwordx4 v136, s[72:73]
	s_waitcnt vmcnt(6)
	s_waitcnt lgkmcnt(0)
	s_barrier
	s_setprio 1
	s_waitcnt lgkmcnt(0)
	v_mfma_f32_16x16x32_bf16 v[62:65], v[154:157], v[188:191], v[62:65]
	v_mfma_f32_16x16x32_bf16 v[62:65], v[158:161], v[196:199], v[62:65]
	v_mfma_f32_16x16x32_bf16 v[46:49], v[154:157], v[200:203], v[46:49]
	v_mfma_f32_16x16x32_bf16 v[46:49], v[158:161], v[204:207], v[46:49]
	v_mfma_f32_16x16x32_bf16 v[30:33], v[154:157], v[208:211], v[30:33]
	v_mfma_f32_16x16x32_bf16 v[30:33], v[158:161], v[212:215], v[30:33]
	v_mfma_f32_16x16x32_bf16 v[14:17], v[154:157], v[216:219], v[14:17]
	v_mfma_f32_16x16x32_bf16 v[14:17], v[158:161], v[220:223], v[14:17]
	v_mfma_f32_16x16x32_bf16 v[6:9], v[162:165], v[216:219], v[6:9]
	v_mfma_f32_16x16x32_bf16 v[6:9], v[166:169], v[220:223], v[6:9]
	v_mfma_f32_16x16x32_bf16 v[22:25], v[162:165], v[208:211], v[22:25]
	v_mfma_f32_16x16x32_bf16 v[22:25], v[166:169], v[212:215], v[22:25]
	v_mfma_f32_16x16x32_bf16 v[38:41], v[162:165], v[200:203], v[38:41]
	v_mfma_f32_16x16x32_bf16 v[38:41], v[166:169], v[204:207], v[38:41]
	v_mfma_f32_16x16x32_bf16 v[54:57], v[162:165], v[188:191], v[54:57]
	v_mfma_f32_16x16x32_bf16 v[54:57], v[166:169], v[196:199], v[54:57]
	s_setprio 0
	s_setprio 1
	v_mfma_f32_16x16x32_bf16 v[58:61], v[170:173], v[188:191], v[58:61]
	v_mfma_f32_16x16x32_bf16 v[58:61], v[174:177], v[196:199], v[58:61]
	v_mfma_f32_16x16x32_bf16 v[42:45], v[170:173], v[200:203], v[42:45]
	v_mfma_f32_16x16x32_bf16 v[42:45], v[174:177], v[204:207], v[42:45]
	v_mfma_f32_16x16x32_bf16 v[26:29], v[170:173], v[208:211], v[26:29]
	v_mfma_f32_16x16x32_bf16 v[26:29], v[174:177], v[212:215], v[26:29]
	v_mfma_f32_16x16x32_bf16 v[10:13], v[170:173], v[216:219], v[10:13]
	v_mfma_f32_16x16x32_bf16 v[10:13], v[174:177], v[220:223], v[10:13]
	v_mfma_f32_16x16x32_bf16 v[2:5], v[180:183], v[216:219], v[2:5]
	v_mfma_f32_16x16x32_bf16 v[2:5], v[184:187], v[220:223], v[2:5]
	v_mfma_f32_16x16x32_bf16 v[18:21], v[180:183], v[208:211], v[18:21]
	v_mfma_f32_16x16x32_bf16 v[18:21], v[184:187], v[212:215], v[18:21]
	v_mfma_f32_16x16x32_bf16 v[34:37], v[180:183], v[200:203], v[34:37]
	v_mfma_f32_16x16x32_bf16 v[34:37], v[184:187], v[204:207], v[34:37]
	v_mfma_f32_16x16x32_bf16 v[50:53], v[180:183], v[188:191], v[50:53]
	v_mfma_f32_16x16x32_bf16 v[50:53], v[184:187], v[196:199], v[50:53]
	s_setprio 0
	s_barrier
	s_add_i32 s76, s76, 2
	s_add_u32 s48, s48, 0x10000
	s_addc_u32 s49, s49, 0
	s_add_u32 s68, s68, 0x10000
	s_addc_u32 s69, s69, 0
	s_cmp_gt_u32 s76, 61
	s_cbranch_scc0 .LBB0_115
	s_and_b64 vcc, exec, s[14:15]
	s_cbranch_vccz .LBB0_118
	s_barrier

; #define PG8_STAGE(bufoff, gbase, voff) do { _Pragma("unroll") for (int _i = 0; _i < 2; ++_i) \
;         __builtin_amdgcn_global_load_lds((const unsigned*)((const char*)(gbase) + (voff)[_i]), (PG8_LAS unsigned*)(lds + (bufoff) + ldsw + _i * 8192), 16, 0, 0); } while (0)
; #define PG8_LDA(dst, b, h) do { _Pragma("unroll") for (int m = 0; m < 4; ++m) _Pragma("unroll") for (int k = 0; k < 2; ++k) dst[m][k] = *(const PG8_LAS bf16x8*)(lds + PG8_SA(b, h) + aoff + m * 2048 + k * 1024); } while (0)
; #define PG8_LDB(dst, b, h) do { _Pragma("unroll") for (int n = 0; n < 2; ++n) _Pragma("unroll") for (int k = 0; k < 2; ++k) dst[n][k] = *(const PG8_LAS bf16x8*)(lds + PG8_SB(b, h) + boff + n * 2048 + k * 1024); } while (0)
; #define PG8_MMA(ai, bj, At, Bt) do { __builtin_amdgcn_s_setprio(1); _Pragma("unroll") for (int m = 0; m < 4; ++m) _Pragma("unroll") for (int n = 0; n < 2; ++n) _Pragma("unroll") for (int k = 0; k < 2; ++k) \
;         acc[ai][bj][m][n] = __builtin_amdgcn_mfma_f32_16x16x32_bf16(Bt[n][k], At[m][k], acc[ai][bj][m][n], 0, 0, 0); __builtin_amdgcn_s_setprio(0); } while (0)
; #define PG8_WAIT_V(n) asm volatile("s_waitcnt vmcnt(" #n ")" ::: "memory")
; #define PG8_WAIT_L(n) asm volatile("s_waitcnt lgkmcnt(" #n ")" ::: "memory")
; template <class Epi, class Sched, bool ALIGN_EPI = false, bool SP2 = false>
; __device__ __forceinline__ void gemm_phase(PG8_LAS unsigned char* lds, const Gemm g, const Sched& S, const Epi& E) {
;     ...
;             const bool last = (t == nt - 2);
;             const char* a1 = cA + (size_t)(t + 1) * kstep;
;             const char* a2 = last ? nA : cA + (size_t)(t + 2) * kstep; const char* b2 = last ? nB : cB + (size_t)(t + 2) * kstep;
;             const char* a3 = a2 + kstep; const char* b3 = b2 + kstep;
;             if (last && has_next) S.a_ready(nxt);
;             if constexpr (SP2) {
;             PG8_LDB(B0, 0, 0); PG8_LDB(B1, 0, 1); PG8_SCHED; PG8_LDA(At, 0, 0); PG8_STAGE(PG8_SA(1, 1), a1 + hstep, voffA);
;             PG8_WAIT_V(8); PG8_WAIT_L(0); PG8_BAR; PG8_MMA(0, 0, At, B0); PG8_MMA(0, 1, At, B1); PG8_BAR; PG8_SCHED;
;             PG8_LDA(At, 0, 1); PG8_STAGE(PG8_SB(0, 0), b2, voffB); PG8_STAGE(PG8_SB(0, 1), b2 + hstep, voffB); PG8_STAGE(PG8_SA(0, 0), a2, voffA);
;             PG8_WAIT_V(8); PG8_WAIT_L(0); PG8_BAR; PG8_MMA(1, 0, At, B0); PG8_MMA(1, 1, At, B1); PG8_BAR; PG8_SCHED;
.LBB0_200:
	ds_read_b128 v[148:151], v154
	ds_read_b128 v[158:161], v154 offset:1024
	ds_read_b128 v[162:165], v154 offset:2048
	ds_read_b128 v[166:169], v154 offset:3072
	ds_read_b128 v[170:173], v155
	ds_read_b128 v[174:177], v155 offset:1024
	ds_read_b128 v[180:183], v155 offset:2048
	ds_read_b128 v[184:187], v155 offset:3072
	s_add_u32 s46, s44, 0x4000
	s_addc_u32 s47, s45, 0
	s_cmpk_eq_i32 s76, 0xa8
	s_cselect_b32 s50, s6, s46
	s_cselect_b32 s51, s7, s47
	s_cselect_b32 s48, s24, s74
	s_cselect_b32 s49, s25, s75
	s_add_u32 s46, s50, 0x8000
	s_addc_u32 s47, s51, 0
	s_sub_u32 s46, s44, 0x4000
	s_subb_u32 s47, s45, 0
	s_mov_b32 m0, s57
	s_nop 0
	global_load_lds_dwordx4 v130, s[46:47]
	s_mov_b32 m0, s58
	s_nop 0
	global_load_lds_dwordx4 v134, s[46:47]
	s_add_i32 m0, s26, 0xc000
	ds_read_b128 v[188:191], v156
	ds_read_b128 v[196:199], v156 offset:1024
	ds_read_b128 v[200:203], v156 offset:2048
	ds_read_b128 v[204:207], v156 offset:3072
	ds_read_b128 v[208:211], v156 offset:4096
	ds_read_b128 v[212:215], v156 offset:5120
	ds_read_b128 v[216:219], v156 offset:6144
	ds_read_b128 v[220:223], v156 offset:7168
	global_load_lds_dwordx4 v140, s[44:45]
	s_add_i32 m0, s26, 0xe000
	s_nop 0
	global_load_lds_dwordx4 v142, s[44:45]
	s_waitcnt vmcnt(8)
	s_waitcnt lgkmcnt(0)
	s_barrier
	s_setprio 1
	s_waitcnt lgkmcnt(0)
	v_mfma_f32_16x16x32_bf16 v[126:129], v[148:151], v[188:191], v[126:129]
	v_mfma_f32_16x16x32_bf16 v[126:129], v[158:161], v[196:199], v[126:129]
	v_mfma_f32_16x16x32_bf16 v[110:113], v[148:151], v[200:203], v[110:113]
	v_mfma_f32_16x16x32_bf16 v[110:113], v[158:161], v[204:207], v[110:113]
	v_mfma_f32_16x16x32_bf16 v[94:97], v[148:151], v[208:211], v[94:97]
	v_mfma_f32_16x16x32_bf16 v[94:97], v[158:161], v[212:215], v[94:97]
	v_mfma_f32_16x16x32_bf16 v[78:81], v[148:151], v[216:219], v[78:81]
	v_mfma_f32_16x16x32_bf16 v[78:81], v[158:161], v[220:223], v[78:81]
	v_mfma_f32_16x16x32_bf16 v[74:77], v[162:165], v[216:219], v[74:77]
	v_mfma_f32_16x16x32_bf16 v[74:77], v[166:169], v[220:223], v[74:77]
	v_mfma_f32_16x16x32_bf16 v[90:93], v[162:165], v[208:211], v[90:93]
	v_mfma_f32_16x16x32_bf16 v[90:93], v[166:169], v[212:215], v[90:93]
	v_mfma_f32_16x16x32_bf16 v[106:109], v[162:165], v[200:203], v[106:109]
	v_mfma_f32_16x16x32_bf16 v[106:109], v[166:169], v[204:207], v[106:109]
	v_mfma_f32_16x16x32_bf16 v[122:125], v[162:165], v[188:191], v[122:125]
	v_mfma_f32_16x16x32_bf16 v[122:125], v[166:169], v[196:199], v[122:125]
	s_setprio 0
	s_setprio 1
	v_mfma_f32_16x16x32_bf16 v[118:121], v[170:173], v[188:191], v[118:121]
	v_mfma_f32_16x16x32_bf16 v[118:121], v[174:177], v[196:199], v[118:121]
	v_mfma_f32_16x16x32_bf16 v[102:105], v[170:173], v[200:203], v[102:105]
	v_mfma_f32_16x16x32_bf16 v[102:105], v[174:177], v[204:207], v[102:105]
	v_mfma_f32_16x16x32_bf16 v[86:89], v[170:173], v[208:211], v[86:89]
	v_mfma_f32_16x16x32_bf16 v[86:89], v[174:177], v[212:215], v[86:89]
	v_mfma_f32_16x16x32_bf16 v[70:73], v[170:173], v[216:219], v[70:73]
	v_mfma_f32_16x16x32_bf16 v[70:73], v[174:177], v[220:223], v[70:73]
	v_mfma_f32_16x16x32_bf16 v[66:69], v[180:183], v[216:219], v[66:69]
	v_mfma_f32_16x16x32_bf16 v[66:69], v[184:187], v[220:223], v[66:69]
	v_mfma_f32_16x16x32_bf16 v[82:85], v[180:183], v[208:211], v[82:85]
	v_mfma_f32_16x16x32_bf16 v[82:85], v[184:187], v[212:215], v[82:85]
	v_mfma_f32_16x16x32_bf16 v[98:101], v[180:183], v[200:203], v[98:101]
	v_mfma_f32_16x16x32_bf16 v[98:101], v[184:187], v[204:207], v[98:101]
	v_mfma_f32_16x16x32_bf16 v[114:117], v[180:183], v[188:191], v[114:117]
	v_mfma_f32_16x16x32_bf16 v[114:117], v[184:187], v[196:199], v[114:117]
	s_setprio 0
	s_barrier
	s_add_i32 s77, s59, s3
	s_mov_b32 m0, s77
	ds_read_b128 v[188:191], v156 offset:16384
	ds_read_b128 v[196:199], v156 offset:17408
	ds_read_b128 v[200:203], v156 offset:18432
	ds_read_b128 v[204:207], v156 offset:19456
	ds_read_b128 v[208:211], v156 offset:20480
	ds_read_b128 v[212:215], v156 offset:21504
	ds_read_b128 v[216:219], v156 offset:22528
	ds_read_b128 v[220:223], v156 offset:23552
	global_load_lds_dwordx4 v132, s[48:49]
	s_add_i32 m0, s77, 0x2000
	s_add_u32 s78, s48, 0x4000
	v_lshl_add_u64 v[224:225], s[48:49], 0, v[136:137]
	s_addc_u32 s79, s49, 0
	s_add_i32 s77, s61, s3
	global_load_lds_dwordx4 v[224:225], off
	s_mov_b32 m0, s77
	s_nop 0
	global_load_lds_dwordx4 v132, s[78:79]
	s_add_i32 m0, s77, 0x2000
	s_nop 0
	global_load_lds_dwordx4 v136, s[78:79]
	s_waitcnt vmcnt(6)
	s_waitcnt lgkmcnt(0)
	s_barrier
	s_setprio 1
	s_waitcnt lgkmcnt(0)
	v_mfma_f32_16x16x32_bf16 v[62:65], v[148:151], v[188:191], v[62:65]
	v_mfma_f32_16x16x32_bf16 v[62:65], v[158:161], v[196:199], v[62:65]
	v_mfma_f32_16x16x32_bf16 v[46:49], v[148:151], v[200:203], v[46:49]
	v_mfma_f32_16x16x32_bf16 v[46:49], v[158:161], v[204:207], v[46:49]
	v_mfma_f32_16x16x32_bf16 v[30:33], v[148:151], v[208:211], v[30:33]
	v_mfma_f32_16x16x32_bf16 v[30:33], v[158:161], v[212:215], v[30:33]
	v_mfma_f32_16x16x32_bf16 v[14:17], v[148:151], v[216:219], v[14:17]
	v_mfma_f32_16x16x32_bf16 v[14:17], v[158:161], v[220:223], v[14:17]
	v_mfma_f32_16x16x32_bf16 v[10:13], v[162:165], v[216:219], v[10:13]
	v_mfma_f32_16x16x32_bf16 v[10:13], v[166:169], v[220:223], v[10:13]
	v_mfma_f32_16x16x32_bf16 v[26:29], v[162:165], v[208:211], v[26:29]
	v_mfma_f32_16x16x32_bf16 v[26:29], v[166:169], v[212:215], v[26:29]
	v_mfma_f32_16x16x32_bf16 v[42:45], v[162:165], v[200:203], v[42:45]
	v_mfma_f32_16x16x32_bf16 v[42:45], v[166:169], v[204:207], v[42:45]
	v_mfma_f32_16x16x32_bf16 v[58:61], v[162:165], v[188:191], v[58:61]
	v_mfma_f32_16x16x32_bf16 v[58:61], v[166:169], v[196:199], v[58:61]
	s_setprio 0
	s_setprio 1
	v_mfma_f32_16x16x32_bf16 v[54:57], v[170:173], v[188:191], v[54:57]
	v_mfma_f32_16x16x32_bf16 v[54:57], v[174:177], v[196:199], v[54:57]
	v_mfma_f32_16x16x32_bf16 v[38:41], v[170:173], v[200:203], v[38:41]
	v_mfma_f32_16x16x32_bf16 v[38:41], v[174:177], v[204:207], v[38:41]
	v_mfma_f32_16x16x32_bf16 v[22:25], v[170:173], v[208:211], v[22:25]
	v_mfma_f32_16x16x32_bf16 v[22:25], v[174:177], v[212:215], v[22:25]
	v_mfma_f32_16x16x32_bf16 v[6:9], v[170:173], v[216:219], v[6:9]
	v_mfma_f32_16x16x32_bf16 v[6:9], v[174:177], v[220:223], v[6:9]
	v_mfma_f32_16x16x32_bf16 v[2:5], v[180:183], v[216:219], v[2:5]
	v_mfma_f32_16x16x32_bf16 v[2:5], v[184:187], v[220:223], v[2:5]
	v_mfma_f32_16x16x32_bf16 v[18:21], v[180:183], v[208:211], v[18:21]
	v_mfma_f32_16x16x32_bf16 v[18:21], v[184:187], v[212:215], v[18:21]
	v_mfma_f32_16x16x32_bf16 v[34:37], v[180:183], v[200:203], v[34:37]
	v_mfma_f32_16x16x32_bf16 v[34:37], v[184:187], v[204:207], v[34:37]
	v_mfma_f32_16x16x32_bf16 v[50:53], v[180:183], v[188:191], v[50:53]
	v_mfma_f32_16x16x32_bf16 v[50:53], v[184:187], v[196:199], v[50:53]
	s_setprio 0
	s_barrier
; #define PG8_STAGE(bufoff, gbase, voff) do { _Pragma("unroll") for (int _i = 0; _i < 2; ++_i) \
;         __builtin_amdgcn_global_load_lds((const unsigned*)((const char*)(gbase) + (voff)[_i]), (PG8_LAS unsigned*)(lds + (bufoff) + ldsw + _i * 8192), 16, 0, 0); } while (0)
; #define PG8_LDA(dst, b, h) do { _Pragma("unroll") for (int m = 0; m < 4; ++m) _Pragma("unroll") for (int k = 0; k < 2; ++k) dst[m][k] = *(const PG8_LAS bf16x8*)(lds + PG8_SA(b, h) + aoff + m * 2048 + k * 1024); } while (0)
; #define PG8_LDB(dst, b, h) do { _Pragma("unroll") for (int n = 0; n < 2; ++n) _Pragma("unroll") for (int k = 0; k < 2; ++k) dst[n][k] = *(const PG8_LAS bf16x8*)(lds + PG8_SB(b, h) + boff + n * 2048 + k * 1024); } while (0)
; #define PG8_MMA(ai, bj, At, Bt) do { __builtin_amdgcn_s_setprio(1); _Pragma("unroll") for (int m = 0; m < 4; ++m) _Pragma("unroll") for (int n = 0; n < 2; ++n) _Pragma("unroll") for (int k = 0; k < 2; ++k) \
;         acc[ai][bj][m][n] = __builtin_amdgcn_mfma_f32_16x16x32_bf16(Bt[n][k], At[m][k], acc[ai][bj][m][n], 0, 0, 0); __builtin_amdgcn_s_setprio(0); } while (0)
; #define PG8_WAIT_V(n) asm volatile("s_waitcnt vmcnt(" #n ")" ::: "memory")
; #define PG8_WAIT_L(n) asm volatile("s_waitcnt lgkmcnt(" #n ")" ::: "memory")
; #define PG8_BAR __builtin_amdgcn_s_barrier()
; #define PG8_SCHED __builtin_amdgcn_sched_barrier(0)
; template <class Epi, class Sched, bool ALIGN_EPI = false, bool SP2 = false>
; __device__ __forceinline__ void gemm_phase(PG8_LAS unsigned char* lds, const Gemm g, const Sched& S, const Epi& E) {
;     ...
;         for (; t < tend; t += 2) {
;     ...
;             PG8_LDB(B0, 1, 0); PG8_LDB(B1, 1, 1); PG8_SCHED; PG8_LDA(At, 1, 0); PG8_STAGE(PG8_SA(0, 1), a2 + hstep, voffA);
;             PG8_WAIT_V(8); PG8_WAIT_L(0); PG8_BAR; PG8_MMA(0, 0, At, B0); PG8_MMA(0, 1, At, B1); PG8_BAR; PG8_SCHED;
;             PG8_LDA(At, 1, 1); PG8_STAGE(PG8_SB(1, 0), b3, voffB); PG8_STAGE(PG8_SB(1, 1), b3 + hstep, voffB); PG8_STAGE(PG8_SA(1, 0), a3, voffA);
;             PG8_WAIT_V(8); PG8_WAIT_L(0); PG8_BAR; PG8_MMA(1, 0, At, B0); PG8_MMA(1, 1, At, B1); PG8_BAR; PG8_SCHED;
	s_add_i32 s77, 0, 0x18000
	v_add_u32_e32 v138, s77, v153
	s_add_i32 s78, 0, 0x1c000
	ds_read_b128 v[148:151], v138
	ds_read_b128 v[158:161], v138 offset:1024
	ds_read_b128 v[162:165], v138 offset:2048
	ds_read_b128 v[166:169], v138 offset:3072
	v_add_u32_e32 v138, s78, v153
	ds_read_b128 v[170:173], v138
	ds_read_b128 v[174:177], v138 offset:1024
	ds_read_b128 v[180:183], v138 offset:2048
	ds_read_b128 v[184:187], v138 offset:3072
	s_mov_b32 m0, s26
	s_nop 0
	global_load_lds_dwordx4 v130, s[50:51]
	s_mov_b32 m0, s27
	s_nop 0
	global_load_lds_dwordx4 v134, s[50:51]
	s_add_u32 s50, s50, 0x4000
	s_addc_u32 s51, s51, 0
	s_mov_b32 m0, s28
	ds_read_b128 v[188:191], v156 offset:32768
	ds_read_b128 v[196:199], v156 offset:33792
	ds_read_b128 v[200:203], v156 offset:34816
	ds_read_b128 v[204:207], v156 offset:35840
	ds_read_b128 v[208:211], v156 offset:36864
	ds_read_b128 v[212:215], v156 offset:37888
	ds_read_b128 v[216:219], v156 offset:38912
	ds_read_b128 v[220:223], v156 offset:39936
	global_load_lds_dwordx4 v130, s[50:51]
	s_mov_b32 m0, s29
	s_nop 0
	global_load_lds_dwordx4 v134, s[50:51]
	s_waitcnt vmcnt(8)
	s_waitcnt lgkmcnt(0)
	s_barrier
	s_setprio 1
	s_waitcnt lgkmcnt(0)
	v_mfma_f32_16x16x32_bf16 v[126:129], v[148:151], v[188:191], v[126:129]
	v_mfma_f32_16x16x32_bf16 v[126:129], v[158:161], v[196:199], v[126:129]
	v_mfma_f32_16x16x32_bf16 v[110:113], v[148:151], v[200:203], v[110:113]
	v_mfma_f32_16x16x32_bf16 v[110:113], v[158:161], v[204:207], v[110:113]
	v_mfma_f32_16x16x32_bf16 v[94:97], v[148:151], v[208:211], v[94:97]
	v_mfma_f32_16x16x32_bf16 v[94:97], v[158:161], v[212:215], v[94:97]
	v_mfma_f32_16x16x32_bf16 v[78:81], v[148:151], v[216:219], v[78:81]
	v_mfma_f32_16x16x32_bf16 v[78:81], v[158:161], v[220:223], v[78:81]
	v_mfma_f32_16x16x32_bf16 v[74:77], v[162:165], v[216:219], v[74:77]
	v_mfma_f32_16x16x32_bf16 v[74:77], v[166:169], v[220:223], v[74:77]
	v_mfma_f32_16x16x32_bf16 v[90:93], v[162:165], v[208:211], v[90:93]
	v_mfma_f32_16x16x32_bf16 v[90:93], v[166:169], v[212:215], v[90:93]
	v_mfma_f32_16x16x32_bf16 v[106:109], v[162:165], v[200:203], v[106:109]
	v_mfma_f32_16x16x32_bf16 v[106:109], v[166:169], v[204:207], v[106:109]
	v_mfma_f32_16x16x32_bf16 v[122:125], v[162:165], v[188:191], v[122:125]
	v_mfma_f32_16x16x32_bf16 v[122:125], v[166:169], v[196:199], v[122:125]
	s_setprio 0
	s_setprio 1
	v_mfma_f32_16x16x32_bf16 v[118:121], v[170:173], v[188:191], v[118:121]
	v_mfma_f32_16x16x32_bf16 v[118:121], v[174:177], v[196:199], v[118:121]
	v_mfma_f32_16x16x32_bf16 v[102:105], v[170:173], v[200:203], v[102:105]
	v_mfma_f32_16x16x32_bf16 v[102:105], v[174:177], v[204:207], v[102:105]
	v_mfma_f32_16x16x32_bf16 v[86:89], v[170:173], v[208:211], v[86:89]
	v_mfma_f32_16x16x32_bf16 v[86:89], v[174:177], v[212:215], v[86:89]
	v_mfma_f32_16x16x32_bf16 v[70:73], v[170:173], v[216:219], v[70:73]
	v_mfma_f32_16x16x32_bf16 v[70:73], v[174:177], v[220:223], v[70:73]
	v_mfma_f32_16x16x32_bf16 v[66:69], v[180:183], v[216:219], v[66:69]
	v_mfma_f32_16x16x32_bf16 v[66:69], v[184:187], v[220:223], v[66:69]
	v_mfma_f32_16x16x32_bf16 v[82:85], v[180:183], v[208:211], v[82:85]
	v_mfma_f32_16x16x32_bf16 v[82:85], v[184:187], v[212:215], v[82:85]
	v_mfma_f32_16x16x32_bf16 v[98:101], v[180:183], v[200:203], v[98:101]
	v_mfma_f32_16x16x32_bf16 v[98:101], v[184:187], v[204:207], v[98:101]
	v_mfma_f32_16x16x32_bf16 v[114:117], v[180:183], v[188:191], v[114:117]
	v_mfma_f32_16x16x32_bf16 v[114:117], v[184:187], v[196:199], v[114:117]
	s_setprio 0
	s_barrier
	s_add_u32 s50, s48, 0x8000
	s_addc_u32 s51, s49, 0
	s_add_i32 s77, s77, s3
	s_mov_b32 m0, s77
	ds_read_b128 v[188:191], v156 offset:49152
	ds_read_b128 v[196:199], v156 offset:50176
	ds_read_b128 v[200:203], v156 offset:51200
	ds_read_b128 v[204:207], v156 offset:52224
	ds_read_b128 v[208:211], v156 offset:53248
	ds_read_b128 v[212:215], v156 offset:54272
	ds_read_b128 v[216:219], v156 offset:55296
	ds_read_b128 v[220:223], v156 offset:56320
	global_load_lds_dwordx4 v132, s[50:51]
	s_add_i32 m0, s77, 0x2000
	s_add_u32 s48, s48, 0xc000
	v_lshl_add_u64 v[224:225], s[50:51], 0, v[136:137]
	s_addc_u32 s49, s49, 0
	s_add_i32 s50, s78, s3
	global_load_lds_dwordx4 v[224:225], off
	s_mov_b32 m0, s50
	s_nop 0
	global_load_lds_dwordx4 v132, s[48:49]
	s_add_i32 m0, s50, 0x2000
	s_nop 0
	global_load_lds_dwordx4 v136, s[48:49]
	s_waitcnt vmcnt(6)
	s_waitcnt lgkmcnt(0)
	s_barrier
	s_setprio 1
	s_waitcnt lgkmcnt(0)
	v_mfma_f32_16x16x32_bf16 v[62:65], v[148:151], v[188:191], v[62:65]
	v_mfma_f32_16x16x32_bf16 v[62:65], v[158:161], v[196:199], v[62:65]
	v_mfma_f32_16x16x32_bf16 v[46:49], v[148:151], v[200:203], v[46:49]
	v_mfma_f32_16x16x32_bf16 v[46:49], v[158:161], v[204:207], v[46:49]
	v_mfma_f32_16x16x32_bf16 v[30:33], v[148:151], v[208:211], v[30:33]
	v_mfma_f32_16x16x32_bf16 v[30:33], v[158:161], v[212:215], v[30:33]
	v_mfma_f32_16x16x32_bf16 v[14:17], v[148:151], v[216:219], v[14:17]
	v_mfma_f32_16x16x32_bf16 v[14:17], v[158:161], v[220:223], v[14:17]
	v_mfma_f32_16x16x32_bf16 v[10:13], v[162:165], v[216:219], v[10:13]
	v_mfma_f32_16x16x32_bf16 v[10:13], v[166:169], v[220:223], v[10:13]
	v_mfma_f32_16x16x32_bf16 v[26:29], v[162:165], v[208:211], v[26:29]
	v_mfma_f32_16x16x32_bf16 v[26:29], v[166:169], v[212:215], v[26:29]
	v_mfma_f32_16x16x32_bf16 v[42:45], v[162:165], v[200:203], v[42:45]
	v_mfma_f32_16x16x32_bf16 v[42:45], v[166:169], v[204:207], v[42:45]
	v_mfma_f32_16x16x32_bf16 v[58:61], v[162:165], v[188:191], v[58:61]
	v_mfma_f32_16x16x32_bf16 v[58:61], v[166:169], v[196:199], v[58:61]
	s_setprio 0
	s_setprio 1
	v_mfma_f32_16x16x32_bf16 v[54:57], v[170:173], v[188:191], v[54:57]
	v_mfma_f32_16x16x32_bf16 v[54:57], v[174:177], v[196:199], v[54:57]
	v_mfma_f32_16x16x32_bf16 v[38:41], v[170:173], v[200:203], v[38:41]
	v_mfma_f32_16x16x32_bf16 v[38:41], v[174:177], v[204:207], v[38:41]
	v_mfma_f32_16x16x32_bf16 v[22:25], v[170:173], v[208:211], v[22:25]
	v_mfma_f32_16x16x32_bf16 v[22:25], v[174:177], v[212:215], v[22:25]
	v_mfma_f32_16x16x32_bf16 v[6:9], v[170:173], v[216:219], v[6:9]
	v_mfma_f32_16x16x32_bf16 v[6:9], v[174:177], v[220:223], v[6:9]
	v_mfma_f32_16x16x32_bf16 v[2:5], v[180:183], v[216:219], v[2:5]
	v_mfma_f32_16x16x32_bf16 v[2:5], v[184:187], v[220:223], v[2:5]
	v_mfma_f32_16x16x32_bf16 v[18:21], v[180:183], v[208:211], v[18:21]
	v_mfma_f32_16x16x32_bf16 v[18:21], v[184:187], v[212:215], v[18:21]
	v_mfma_f32_16x16x32_bf16 v[34:37], v[180:183], v[200:203], v[34:37]
	v_mfma_f32_16x16x32_bf16 v[34:37], v[184:187], v[204:207], v[34:37]
	v_mfma_f32_16x16x32_bf16 v[50:53], v[180:183], v[188:191], v[50:53]
	v_mfma_f32_16x16x32_bf16 v[50:53], v[184:187], v[196:199], v[50:53]
	s_setprio 0
	s_barrier
	s_add_i32 s76, s76, 2
	s_add_u32 s44, s44, 0x10000
	s_addc_u32 s45, s45, 0
	s_add_u32 s74, s74, 0x10000
	s_addc_u32 s75, s75, 0
	s_cmpk_gt_u32 s76, 0xa9
	s_cbranch_scc0 .LBB0_200
	s_and_b64 vcc, exec, s[18:19]
	s_cbranch_vccz .LBB0_203
	s_barrier

; #define PG8_STAGE(bufoff, gbase, voff) do { _Pragma("unroll") for (int _i = 0; _i < 2; ++_i) \
;         __builtin_amdgcn_global_load_lds((const unsigned*)((const char*)(gbase) + (voff)[_i]), (PG8_LAS unsigned*)(lds + (bufoff) + ldsw + _i * 8192), 16, 0, 0); } while (0)
; #define PG8_LDA(dst, b, h) do { _Pragma("unroll") for (int m = 0; m < 4; ++m) _Pragma("unroll") for (int k = 0; k < 2; ++k) dst[m][k] = *(const PG8_LAS bf16x8*)(lds + PG8_SA(b, h) + aoff + m * 2048 + k * 1024); } while (0)
; #define PG8_LDB(dst, b, h) do { _Pragma("unroll") for (int n = 0; n < 2; ++n) _Pragma("unroll") for (int k = 0; k < 2; ++k) dst[n][k] = *(const PG8_LAS bf16x8*)(lds + PG8_SB(b, h) + boff + n * 2048 + k * 1024); } while (0)
; #define PG8_MMA(ai, bj, At, Bt) do { __builtin_amdgcn_s_setprio(1); _Pragma("unroll") for (int m = 0; m < 4; ++m) _Pragma("unroll") for (int n = 0; n < 2; ++n) _Pragma("unroll") for (int k = 0; k < 2; ++k) \
;         acc[ai][bj][m][n] = __builtin_amdgcn_mfma_f32_16x16x32_bf16(Bt[n][k], At[m][k], acc[ai][bj][m][n], 0, 0, 0); __builtin_amdgcn_s_setprio(0); } while (0)
; #define PG8_WAIT_V(n) asm volatile("s_waitcnt vmcnt(" #n ")" ::: "memory")
; #define PG8_WAIT_L(n) asm volatile("s_waitcnt lgkmcnt(" #n ")" ::: "memory")
; template <class Epi, class Sched, bool ALIGN_EPI = false, bool SP2 = false>
; __device__ __forceinline__ void gemm_phase(PG8_LAS unsigned char* lds, const Gemm g, const Sched& S, const Epi& E) {
;     ...
;             const bool last = (t == nt - 2);
;             const char* a1 = cA + (size_t)(t + 1) * kstep;
;             const char* a2 = last ? nA : cA + (size_t)(t + 2) * kstep; const char* b2 = last ? nB : cB + (size_t)(t + 2) * kstep;
;             const char* a3 = a2 + kstep; const char* b3 = b2 + kstep;
;             if (last && has_next) S.a_ready(nxt);
;             if constexpr (SP2) {
;             PG8_LDB(B0, 0, 0); PG8_LDB(B1, 0, 1); PG8_SCHED; PG8_LDA(At, 0, 0); PG8_STAGE(PG8_SA(1, 1), a1 + hstep, voffA);
;             PG8_WAIT_V(8); PG8_WAIT_L(0); PG8_BAR; PG8_MMA(0, 0, At, B0); PG8_MMA(0, 1, At, B1); PG8_BAR; PG8_SCHED;
;             PG8_LDA(At, 0, 1); PG8_STAGE(PG8_SB(0, 0), b2, voffB); PG8_STAGE(PG8_SB(0, 1), b2 + hstep, voffB); PG8_STAGE(PG8_SA(0, 0), a2, voffA);
;             PG8_WAIT_V(8); PG8_WAIT_L(0); PG8_BAR; PG8_MMA(1, 0, At, B0); PG8_MMA(1, 1, At, B1); PG8_BAR; PG8_SCHED;
.LBB0_290:
	ds_read_b128 v[146:149], v162
	ds_read_b128 v[150:153], v162 offset:1024
	ds_read_b128 v[154:157], v162 offset:2048
	ds_read_b128 v[168:171], v162 offset:3072
	ds_read_b128 v[172:175], v163
	ds_read_b128 v[180:183], v163 offset:1024
	ds_read_b128 v[184:187], v163 offset:2048
	ds_read_b128 v[188:191], v163 offset:3072
	s_add_u32 s59, s72, 0x4000
	s_addc_u32 s62, s73, 0
	s_cmp_eq_u32 s58, 60
	s_cselect_b32 s78, s19, s59
	s_cselect_b32 s79, s5, s62
	s_cselect_b32 s76, s26, s33
	s_cselect_b32 s77, s17, s56
	s_add_u32 s74, s78, 0x8000
	s_addc_u32 s75, s79, 0
	s_sub_u32 s74, s72, 0x4000
	s_subb_u32 s75, s73, 0
	s_mov_b32 m0, s51
	s_nop 0
	global_load_lds_dwordx4 v130, s[74:75]
	s_mov_b32 m0, s57
	s_nop 0
	global_load_lds_dwordx4 v134, s[74:75]
	s_add_i32 m0, s15, 0xc000
	ds_read_b128 v[198:201], v164
	ds_read_b128 v[202:205], v164 offset:1024
	ds_read_b128 v[206:209], v164 offset:2048
	ds_read_b128 v[210:213], v164 offset:3072
	ds_read_b128 v[214:217], v164 offset:4096
	ds_read_b128 v[218:221], v164 offset:5120
	ds_read_b128 v[222:225], v164 offset:6144
	ds_read_b128 v[226:229], v164 offset:7168
	global_load_lds_dwordx4 v138, s[72:73]
	s_add_i32 m0, s15, 0xe000
	s_nop 0
	global_load_lds_dwordx4 v140, s[72:73]
	s_waitcnt vmcnt(8)
	s_waitcnt lgkmcnt(0)
	s_barrier
	s_setprio 1
	s_waitcnt lgkmcnt(0)
	v_mfma_f32_16x16x32_bf16 v[126:129], v[146:149], v[198:201], v[126:129]
	v_mfma_f32_16x16x32_bf16 v[126:129], v[150:153], v[202:205], v[126:129]
	v_mfma_f32_16x16x32_bf16 v[110:113], v[146:149], v[206:209], v[110:113]
	v_mfma_f32_16x16x32_bf16 v[110:113], v[150:153], v[210:213], v[110:113]
	v_mfma_f32_16x16x32_bf16 v[94:97], v[146:149], v[214:217], v[94:97]
	v_mfma_f32_16x16x32_bf16 v[94:97], v[150:153], v[218:221], v[94:97]
	v_mfma_f32_16x16x32_bf16 v[78:81], v[146:149], v[222:225], v[78:81]
	v_mfma_f32_16x16x32_bf16 v[78:81], v[150:153], v[226:229], v[78:81]
	v_mfma_f32_16x16x32_bf16 v[74:77], v[154:157], v[222:225], v[74:77]
	v_mfma_f32_16x16x32_bf16 v[74:77], v[168:171], v[226:229], v[74:77]
	v_mfma_f32_16x16x32_bf16 v[90:93], v[154:157], v[214:217], v[90:93]
	v_mfma_f32_16x16x32_bf16 v[90:93], v[168:171], v[218:221], v[90:93]
	v_mfma_f32_16x16x32_bf16 v[106:109], v[154:157], v[206:209], v[106:109]
	v_mfma_f32_16x16x32_bf16 v[106:109], v[168:171], v[210:213], v[106:109]
	v_mfma_f32_16x16x32_bf16 v[122:125], v[154:157], v[198:201], v[122:125]
	v_mfma_f32_16x16x32_bf16 v[122:125], v[168:171], v[202:205], v[122:125]
	s_setprio 0
	s_setprio 1
	v_mfma_f32_16x16x32_bf16 v[118:121], v[172:175], v[198:201], v[118:121]
	v_mfma_f32_16x16x32_bf16 v[118:121], v[180:183], v[202:205], v[118:121]
	v_mfma_f32_16x16x32_bf16 v[102:105], v[172:175], v[206:209], v[102:105]
	v_mfma_f32_16x16x32_bf16 v[102:105], v[180:183], v[210:213], v[102:105]
	v_mfma_f32_16x16x32_bf16 v[86:89], v[172:175], v[214:217], v[86:89]
	v_mfma_f32_16x16x32_bf16 v[86:89], v[180:183], v[218:221], v[86:89]
	v_mfma_f32_16x16x32_bf16 v[70:73], v[172:175], v[222:225], v[70:73]
	v_mfma_f32_16x16x32_bf16 v[70:73], v[180:183], v[226:229], v[70:73]
	v_mfma_f32_16x16x32_bf16 v[66:69], v[184:187], v[222:225], v[66:69]
	v_mfma_f32_16x16x32_bf16 v[66:69], v[188:191], v[226:229], v[66:69]
	v_mfma_f32_16x16x32_bf16 v[82:85], v[184:187], v[214:217], v[82:85]
	v_mfma_f32_16x16x32_bf16 v[82:85], v[188:191], v[218:221], v[82:85]
	v_mfma_f32_16x16x32_bf16 v[98:101], v[184:187], v[206:209], v[98:101]
	v_mfma_f32_16x16x32_bf16 v[98:101], v[188:191], v[210:213], v[98:101]
	v_mfma_f32_16x16x32_bf16 v[114:117], v[184:187], v[198:201], v[114:117]
	v_mfma_f32_16x16x32_bf16 v[114:117], v[188:191], v[202:205], v[114:117]
	s_setprio 0
	s_barrier
	s_add_i32 s59, s81, s3
	s_mov_b32 m0, s59
	ds_read_b128 v[198:201], v164 offset:16384
	ds_read_b128 v[202:205], v164 offset:17408
	ds_read_b128 v[206:209], v164 offset:18432
	ds_read_b128 v[210:213], v164 offset:19456
	ds_read_b128 v[214:217], v164 offset:20480
	ds_read_b128 v[218:221], v164 offset:21504
	ds_read_b128 v[222:225], v164 offset:22528
	ds_read_b128 v[226:229], v164 offset:23552
	global_load_lds_dwordx4 v132, s[76:77]
	s_add_i32 m0, s59, 0x2000
	s_add_u32 s62, s76, 0x4000
	v_lshl_add_u64 v[158:159], s[76:77], 0, v[136:137]
	s_addc_u32 s63, s77, 0
	s_add_i32 s59, s82, s3
	global_load_lds_dwordx4 v[158:159], off
	s_mov_b32 m0, s59
	s_nop 0
	global_load_lds_dwordx4 v132, s[62:63]
	s_add_i32 m0, s59, 0x2000
	s_nop 0
	global_load_lds_dwordx4 v136, s[62:63]
	s_waitcnt vmcnt(6)
	s_waitcnt lgkmcnt(0)
	s_barrier
	s_setprio 1
	s_waitcnt lgkmcnt(0)
	v_mfma_f32_16x16x32_bf16 v[62:65], v[146:149], v[198:201], v[62:65]
	v_mfma_f32_16x16x32_bf16 v[62:65], v[150:153], v[202:205], v[62:65]
	v_mfma_f32_16x16x32_bf16 v[46:49], v[146:149], v[206:209], v[46:49]
	v_mfma_f32_16x16x32_bf16 v[46:49], v[150:153], v[210:213], v[46:49]
	v_mfma_f32_16x16x32_bf16 v[30:33], v[146:149], v[214:217], v[30:33]
	v_mfma_f32_16x16x32_bf16 v[30:33], v[150:153], v[218:221], v[30:33]
	v_mfma_f32_16x16x32_bf16 v[14:17], v[146:149], v[222:225], v[14:17]
	v_mfma_f32_16x16x32_bf16 v[14:17], v[150:153], v[226:229], v[14:17]
	v_mfma_f32_16x16x32_bf16 v[10:13], v[154:157], v[222:225], v[10:13]
	v_mfma_f32_16x16x32_bf16 v[10:13], v[168:171], v[226:229], v[10:13]
	v_mfma_f32_16x16x32_bf16 v[26:29], v[154:157], v[214:217], v[26:29]
	v_mfma_f32_16x16x32_bf16 v[26:29], v[168:171], v[218:221], v[26:29]
	v_mfma_f32_16x16x32_bf16 v[42:45], v[154:157], v[206:209], v[42:45]
	v_mfma_f32_16x16x32_bf16 v[42:45], v[168:171], v[210:213], v[42:45]
	v_mfma_f32_16x16x32_bf16 v[58:61], v[154:157], v[198:201], v[58:61]
	v_mfma_f32_16x16x32_bf16 v[58:61], v[168:171], v[202:205], v[58:61]
	s_setprio 0
	s_setprio 1
	v_mfma_f32_16x16x32_bf16 v[54:57], v[172:175], v[198:201], v[54:57]
	v_mfma_f32_16x16x32_bf16 v[54:57], v[180:183], v[202:205], v[54:57]
	v_mfma_f32_16x16x32_bf16 v[38:41], v[172:175], v[206:209], v[38:41]
	v_mfma_f32_16x16x32_bf16 v[38:41], v[180:183], v[210:213], v[38:41]
	v_mfma_f32_16x16x32_bf16 v[22:25], v[172:175], v[214:217], v[22:25]
	v_mfma_f32_16x16x32_bf16 v[22:25], v[180:183], v[218:221], v[22:25]
	v_mfma_f32_16x16x32_bf16 v[6:9], v[172:175], v[222:225], v[6:9]
	v_mfma_f32_16x16x32_bf16 v[6:9], v[180:183], v[226:229], v[6:9]
	v_mfma_f32_16x16x32_bf16 v[2:5], v[184:187], v[222:225], v[2:5]
	v_mfma_f32_16x16x32_bf16 v[2:5], v[188:191], v[226:229], v[2:5]
	v_mfma_f32_16x16x32_bf16 v[18:21], v[184:187], v[214:217], v[18:21]
	v_mfma_f32_16x16x32_bf16 v[18:21], v[188:191], v[218:221], v[18:21]
	v_mfma_f32_16x16x32_bf16 v[34:37], v[184:187], v[206:209], v[34:37]
	v_mfma_f32_16x16x32_bf16 v[34:37], v[188:191], v[210:213], v[34:37]
	v_mfma_f32_16x16x32_bf16 v[50:53], v[184:187], v[198:201], v[50:53]
	v_mfma_f32_16x16x32_bf16 v[50:53], v[188:191], v[202:205], v[50:53]
	s_setprio 0
	s_barrier
; #define PG8_STAGE(bufoff, gbase, voff) do { _Pragma("unroll") for (int _i = 0; _i < 2; ++_i) \
;         __builtin_amdgcn_global_load_lds((const unsigned*)((const char*)(gbase) + (voff)[_i]), (PG8_LAS unsigned*)(lds + (bufoff) + ldsw + _i * 8192), 16, 0, 0); } while (0)
; #define PG8_LDA(dst, b, h) do { _Pragma("unroll") for (int m = 0; m < 4; ++m) _Pragma("unroll") for (int k = 0; k < 2; ++k) dst[m][k] = *(const PG8_LAS bf16x8*)(lds + PG8_SA(b, h) + aoff + m * 2048 + k * 1024); } while (0)
; #define PG8_LDB(dst, b, h) do { _Pragma("unroll") for (int n = 0; n < 2; ++n) _Pragma("unroll") for (int k = 0; k < 2; ++k) dst[n][k] = *(const PG8_LAS bf16x8*)(lds + PG8_SB(b, h) + boff + n * 2048 + k * 1024); } while (0)
; #define PG8_MMA(ai, bj, At, Bt) do { __builtin_amdgcn_s_setprio(1); _Pragma("unroll") for (int m = 0; m < 4; ++m) _Pragma("unroll") for (int n = 0; n < 2; ++n) _Pragma("unroll") for (int k = 0; k < 2; ++k) \
;         acc[ai][bj][m][n] = __builtin_amdgcn_mfma_f32_16x16x32_bf16(Bt[n][k], At[m][k], acc[ai][bj][m][n], 0, 0, 0); __builtin_amdgcn_s_setprio(0); } while (0)
; #define PG8_WAIT_V(n) asm volatile("s_waitcnt vmcnt(" #n ")" ::: "memory")
; #define PG8_WAIT_L(n) asm volatile("s_waitcnt lgkmcnt(" #n ")" ::: "memory")
; #define PG8_BAR __builtin_amdgcn_s_barrier()
; #define PG8_SCHED __builtin_amdgcn_sched_barrier(0)
; template <class Epi, class Sched, bool ALIGN_EPI = false, bool SP2 = false>
; __device__ __forceinline__ void gemm_phase(PG8_LAS unsigned char* lds, const Gemm g, const Sched& S, const Epi& E) {
;     ...
;         for (; t < tend; t += 2) {
;     ...
;             PG8_LDB(B0, 1, 0); PG8_LDB(B1, 1, 1); PG8_SCHED; PG8_LDA(At, 1, 0); PG8_STAGE(PG8_SA(0, 1), a2 + hstep, voffA);
;             PG8_WAIT_V(8); PG8_WAIT_L(0); PG8_BAR; PG8_MMA(0, 0, At, B0); PG8_MMA(0, 1, At, B1); PG8_BAR; PG8_SCHED;
;             PG8_LDA(At, 1, 1); PG8_STAGE(PG8_SB(1, 0), b3, voffB); PG8_STAGE(PG8_SB(1, 1), b3 + hstep, voffB); PG8_STAGE(PG8_SA(1, 0), a3, voffA);
;             PG8_WAIT_V(8); PG8_WAIT_L(0); PG8_BAR; PG8_MMA(1, 0, At, B0); PG8_MMA(1, 1, At, B1); PG8_BAR; PG8_SCHED;
	s_add_i32 s59, 0, 0x18000
	v_add_u32_e32 v158, s59, v160
	s_add_i32 s64, 0, 0x1c000
	ds_read_b128 v[146:149], v158
	ds_read_b128 v[150:153], v158 offset:1024
	ds_read_b128 v[154:157], v158 offset:2048
	ds_read_b128 v[168:171], v158 offset:3072
	v_add_u32_e32 v158, s64, v160
	ds_read_b128 v[172:175], v158
	ds_read_b128 v[180:183], v158 offset:1024
	ds_read_b128 v[184:187], v158 offset:2048
	ds_read_b128 v[188:191], v158 offset:3072
	s_mov_b32 m0, s15
	s_nop 0
	global_load_lds_dwordx4 v130, s[78:79]
	s_mov_b32 m0, s27
	s_nop 0
	global_load_lds_dwordx4 v134, s[78:79]
	s_add_u32 s62, s78, 0x4000
	s_addc_u32 s63, s79, 0
	s_mov_b32 m0, s28
	ds_read_b128 v[198:201], v164 offset:32768
	ds_read_b128 v[202:205], v164 offset:33792
	ds_read_b128 v[206:209], v164 offset:34816
	ds_read_b128 v[210:213], v164 offset:35840
	ds_read_b128 v[214:217], v164 offset:36864
	ds_read_b128 v[218:221], v164 offset:37888
	ds_read_b128 v[222:225], v164 offset:38912
	ds_read_b128 v[226:229], v164 offset:39936
	global_load_lds_dwordx4 v130, s[62:63]
	s_mov_b32 m0, s29
	s_nop 0
	global_load_lds_dwordx4 v134, s[62:63]
	s_waitcnt vmcnt(8)
	s_waitcnt lgkmcnt(0)
	s_barrier
	s_setprio 1
	s_waitcnt lgkmcnt(0)
	v_mfma_f32_16x16x32_bf16 v[126:129], v[146:149], v[198:201], v[126:129]
	v_mfma_f32_16x16x32_bf16 v[126:129], v[150:153], v[202:205], v[126:129]
	v_mfma_f32_16x16x32_bf16 v[110:113], v[146:149], v[206:209], v[110:113]
	v_mfma_f32_16x16x32_bf16 v[110:113], v[150:153], v[210:213], v[110:113]
	v_mfma_f32_16x16x32_bf16 v[94:97], v[146:149], v[214:217], v[94:97]
	v_mfma_f32_16x16x32_bf16 v[94:97], v[150:153], v[218:221], v[94:97]
	v_mfma_f32_16x16x32_bf16 v[78:81], v[146:149], v[222:225], v[78:81]
	v_mfma_f32_16x16x32_bf16 v[78:81], v[150:153], v[226:229], v[78:81]
	v_mfma_f32_16x16x32_bf16 v[74:77], v[154:157], v[222:225], v[74:77]
	v_mfma_f32_16x16x32_bf16 v[74:77], v[168:171], v[226:229], v[74:77]
	v_mfma_f32_16x16x32_bf16 v[90:93], v[154:157], v[214:217], v[90:93]
	v_mfma_f32_16x16x32_bf16 v[90:93], v[168:171], v[218:221], v[90:93]
	v_mfma_f32_16x16x32_bf16 v[106:109], v[154:157], v[206:209], v[106:109]
	v_mfma_f32_16x16x32_bf16 v[106:109], v[168:171], v[210:213], v[106:109]
	v_mfma_f32_16x16x32_bf16 v[122:125], v[154:157], v[198:201], v[122:125]
	v_mfma_f32_16x16x32_bf16 v[122:125], v[168:171], v[202:205], v[122:125]
	s_setprio 0
	s_setprio 1
	v_mfma_f32_16x16x32_bf16 v[118:121], v[172:175], v[198:201], v[118:121]
	v_mfma_f32_16x16x32_bf16 v[118:121], v[180:183], v[202:205], v[118:121]
	v_mfma_f32_16x16x32_bf16 v[102:105], v[172:175], v[206:209], v[102:105]
	v_mfma_f32_16x16x32_bf16 v[102:105], v[180:183], v[210:213], v[102:105]
	v_mfma_f32_16x16x32_bf16 v[86:89], v[172:175], v[214:217], v[86:89]
	v_mfma_f32_16x16x32_bf16 v[86:89], v[180:183], v[218:221], v[86:89]
	v_mfma_f32_16x16x32_bf16 v[70:73], v[172:175], v[222:225], v[70:73]
	v_mfma_f32_16x16x32_bf16 v[70:73], v[180:183], v[226:229], v[70:73]
	v_mfma_f32_16x16x32_bf16 v[66:69], v[184:187], v[222:225], v[66:69]
	v_mfma_f32_16x16x32_bf16 v[66:69], v[188:191], v[226:229], v[66:69]
	v_mfma_f32_16x16x32_bf16 v[82:85], v[184:187], v[214:217], v[82:85]
	v_mfma_f32_16x16x32_bf16 v[82:85], v[188:191], v[218:221], v[82:85]
	v_mfma_f32_16x16x32_bf16 v[98:101], v[184:187], v[206:209], v[98:101]
	v_mfma_f32_16x16x32_bf16 v[98:101], v[188:191], v[210:213], v[98:101]
	v_mfma_f32_16x16x32_bf16 v[114:117], v[184:187], v[198:201], v[114:117]
	v_mfma_f32_16x16x32_bf16 v[114:117], v[188:191], v[202:205], v[114:117]
	s_setprio 0
	s_barrier
	s_add_u32 s62, s76, 0x8000
	s_addc_u32 s63, s77, 0
	s_add_i32 s59, s59, s3
	s_mov_b32 m0, s59
	ds_read_b128 v[198:201], v164 offset:49152
	ds_read_b128 v[202:205], v164 offset:50176
	ds_read_b128 v[206:209], v164 offset:51200
	ds_read_b128 v[210:213], v164 offset:52224
	ds_read_b128 v[214:217], v164 offset:53248
	ds_read_b128 v[218:221], v164 offset:54272
	ds_read_b128 v[222:225], v164 offset:55296
	ds_read_b128 v[226:229], v164 offset:56320
	global_load_lds_dwordx4 v132, s[62:63]
	s_add_i32 m0, s59, 0x2000
	v_lshl_add_u64 v[158:159], s[62:63], 0, v[136:137]
	s_add_u32 s62, s76, 0xc000
	s_addc_u32 s63, s77, 0
	s_add_i32 s59, s64, s3
	global_load_lds_dwordx4 v[158:159], off
	s_mov_b32 m0, s59
	s_nop 0
	global_load_lds_dwordx4 v132, s[62:63]
	s_add_i32 m0, s59, 0x2000
	s_nop 0
	global_load_lds_dwordx4 v136, s[62:63]
	s_waitcnt vmcnt(6)
	s_waitcnt lgkmcnt(0)
	s_barrier
	s_setprio 1
	s_waitcnt lgkmcnt(0)
	v_mfma_f32_16x16x32_bf16 v[62:65], v[146:149], v[198:201], v[62:65]
	v_mfma_f32_16x16x32_bf16 v[62:65], v[150:153], v[202:205], v[62:65]
	v_mfma_f32_16x16x32_bf16 v[46:49], v[146:149], v[206:209], v[46:49]
	v_mfma_f32_16x16x32_bf16 v[46:49], v[150:153], v[210:213], v[46:49]
	v_mfma_f32_16x16x32_bf16 v[30:33], v[146:149], v[214:217], v[30:33]
	v_mfma_f32_16x16x32_bf16 v[30:33], v[150:153], v[218:221], v[30:33]
	v_mfma_f32_16x16x32_bf16 v[14:17], v[146:149], v[222:225], v[14:17]
	v_mfma_f32_16x16x32_bf16 v[14:17], v[150:153], v[226:229], v[14:17]
	v_mfma_f32_16x16x32_bf16 v[10:13], v[154:157], v[222:225], v[10:13]
	v_mfma_f32_16x16x32_bf16 v[10:13], v[168:171], v[226:229], v[10:13]
	v_mfma_f32_16x16x32_bf16 v[26:29], v[154:157], v[214:217], v[26:29]
	v_mfma_f32_16x16x32_bf16 v[26:29], v[168:171], v[218:221], v[26:29]
	v_mfma_f32_16x16x32_bf16 v[42:45], v[154:157], v[206:209], v[42:45]
	v_mfma_f32_16x16x32_bf16 v[42:45], v[168:171], v[210:213], v[42:45]
	v_mfma_f32_16x16x32_bf16 v[58:61], v[154:157], v[198:201], v[58:61]
	v_mfma_f32_16x16x32_bf16 v[58:61], v[168:171], v[202:205], v[58:61]
	s_setprio 0
	s_setprio 1
	v_mfma_f32_16x16x32_bf16 v[54:57], v[172:175], v[198:201], v[54:57]
	v_mfma_f32_16x16x32_bf16 v[54:57], v[180:183], v[202:205], v[54:57]
	v_mfma_f32_16x16x32_bf16 v[38:41], v[172:175], v[206:209], v[38:41]
	v_mfma_f32_16x16x32_bf16 v[38:41], v[180:183], v[210:213], v[38:41]
	v_mfma_f32_16x16x32_bf16 v[22:25], v[172:175], v[214:217], v[22:25]
	v_mfma_f32_16x16x32_bf16 v[22:25], v[180:183], v[218:221], v[22:25]
	v_mfma_f32_16x16x32_bf16 v[6:9], v[172:175], v[222:225], v[6:9]
	v_mfma_f32_16x16x32_bf16 v[6:9], v[180:183], v[226:229], v[6:9]
	v_mfma_f32_16x16x32_bf16 v[2:5], v[184:187], v[222:225], v[2:5]
	v_mfma_f32_16x16x32_bf16 v[2:5], v[188:191], v[226:229], v[2:5]
	v_mfma_f32_16x16x32_bf16 v[18:21], v[184:187], v[214:217], v[18:21]
	v_mfma_f32_16x16x32_bf16 v[18:21], v[188:191], v[218:221], v[18:21]
	v_mfma_f32_16x16x32_bf16 v[34:37], v[184:187], v[206:209], v[34:37]
	v_mfma_f32_16x16x32_bf16 v[34:37], v[188:191], v[210:213], v[34:37]
	v_mfma_f32_16x16x32_bf16 v[50:53], v[184:187], v[198:201], v[50:53]
	v_mfma_f32_16x16x32_bf16 v[50:53], v[188:191], v[202:205], v[50:53]
	s_setprio 0
	s_barrier
	s_add_i32 s58, s58, 2
	s_add_u32 s72, s72, 0x10000
	s_addc_u32 s73, s73, 0
	s_add_u32 s33, s33, 0x10000
	s_addc_u32 s56, s56, 0
	s_cmp_gt_u32 s58, 61
	s_cbranch_scc0 .LBB0_290
	s_and_b64 vcc, exec, s[12:13]
	s_cbranch_vccz .LBB0_293
	s_barrier

; #define PG8_STAGE(bufoff, gbase, voff) do { _Pragma("unroll") for (int _i = 0; _i < 2; ++_i) \
;         __builtin_amdgcn_global_load_lds((const unsigned*)((const char*)(gbase) + (voff)[_i]), (PG8_LAS unsigned*)(lds + (bufoff) + ldsw + _i * 8192), 16, 0, 0); } while (0)
; #define PG8_LDA(dst, b, h) do { _Pragma("unroll") for (int m = 0; m < 4; ++m) _Pragma("unroll") for (int k = 0; k < 2; ++k) dst[m][k] = *(const PG8_LAS bf16x8*)(lds + PG8_SA(b, h) + aoff + m * 2048 + k * 1024); } while (0)
; #define PG8_LDB(dst, b, h) do { _Pragma("unroll") for (int n = 0; n < 2; ++n) _Pragma("unroll") for (int k = 0; k < 2; ++k) dst[n][k] = *(const PG8_LAS bf16x8*)(lds + PG8_SB(b, h) + boff + n * 2048 + k * 1024); } while (0)
; #define PG8_MMA(ai, bj, At, Bt) do { __builtin_amdgcn_s_setprio(1); _Pragma("unroll") for (int m = 0; m < 4; ++m) _Pragma("unroll") for (int n = 0; n < 2; ++n) _Pragma("unroll") for (int k = 0; k < 2; ++k) \
;         acc[ai][bj][m][n] = __builtin_amdgcn_mfma_f32_16x16x32_bf16(Bt[n][k], At[m][k], acc[ai][bj][m][n], 0, 0, 0); __builtin_amdgcn_s_setprio(0); } while (0)
; #define PG8_WAIT_V(n) asm volatile("s_waitcnt vmcnt(" #n ")" ::: "memory")
; #define PG8_WAIT_L(n) asm volatile("s_waitcnt lgkmcnt(" #n ")" ::: "memory")
; template <class Epi, class Sched, bool ALIGN_EPI = false, bool SP2 = false>
; __device__ __forceinline__ void gemm_phase(PG8_LAS unsigned char* lds, const Gemm g, const Sched& S, const Epi& E) {
;     ...
;             const bool last = (t == nt - 2);
;             const char* a1 = cA + (size_t)(t + 1) * kstep;
;             const char* a2 = last ? nA : cA + (size_t)(t + 2) * kstep; const char* b2 = last ? nB : cB + (size_t)(t + 2) * kstep;
;             const char* a3 = a2 + kstep; const char* b3 = b2 + kstep;
;             if (last && has_next) S.a_ready(nxt);
;             if constexpr (SP2) {
;             PG8_LDB(B0, 0, 0); PG8_LDB(B1, 0, 1); PG8_SCHED; PG8_LDA(At, 0, 0); PG8_STAGE(PG8_SA(1, 1), a1 + hstep, voffA);
;             PG8_WAIT_V(8); PG8_WAIT_L(0); PG8_BAR; PG8_MMA(0, 0, At, B0); PG8_MMA(0, 1, At, B1); PG8_BAR; PG8_SCHED;
;             PG8_LDA(At, 0, 1); PG8_STAGE(PG8_SB(0, 0), b2, voffB); PG8_STAGE(PG8_SB(0, 1), b2 + hstep, voffB); PG8_STAGE(PG8_SA(0, 0), a2, voffA);
;             PG8_WAIT_V(8); PG8_WAIT_L(0); PG8_BAR; PG8_MMA(1, 0, At, B0); PG8_MMA(1, 1, At, B1); PG8_BAR; PG8_SCHED;
.LBB0_757:
	ds_read_b128 v[154:157], v149
	ds_read_b128 v[158:161], v149 offset:1024
	ds_read_b128 v[162:165], v149 offset:2048
	ds_read_b128 v[166:169], v149 offset:3072
	ds_read_b128 v[170:173], v150
	ds_read_b128 v[174:177], v150 offset:1024
	ds_read_b128 v[180:183], v150 offset:2048
	ds_read_b128 v[184:187], v150 offset:3072
	s_add_u32 s46, s44, 0x4000
	s_addc_u32 s47, s45, 0
	s_cmp_eq_u32 s70, 60
	s_cselect_b32 s50, s39, s46
	s_cselect_b32 s51, s17, s47
	s_cselect_b32 s48, s41, s68
	s_cselect_b32 s49, s15, s69
	s_add_u32 s46, s50, 0x8000
	s_addc_u32 s47, s51, 0
	s_sub_u32 s46, s44, 0x4000
	s_subb_u32 s47, s45, 0
	s_mov_b32 m0, s57
	s_nop 0
	global_load_lds_dwordx4 v130, s[46:47]
	s_mov_b32 m0, s58
	s_nop 0
	global_load_lds_dwordx4 v134, s[46:47]
	s_add_i32 m0, s26, 0xc000
	ds_read_b128 v[188:191], v151
	ds_read_b128 v[198:201], v151 offset:1024
	ds_read_b128 v[202:205], v151 offset:2048
	ds_read_b128 v[206:209], v151 offset:3072
	ds_read_b128 v[210:213], v151 offset:4096
	ds_read_b128 v[214:217], v151 offset:5120
	ds_read_b128 v[218:221], v151 offset:6144
	ds_read_b128 v[222:225], v151 offset:7168
	global_load_lds_dwordx4 v138, s[44:45]
	s_add_i32 m0, s26, 0xe000
	s_nop 0
	global_load_lds_dwordx4 v140, s[44:45]
	s_waitcnt vmcnt(8)
	s_waitcnt lgkmcnt(0)
	s_barrier
	s_setprio 1
	s_waitcnt lgkmcnt(0)
	v_mfma_f32_16x16x32_bf16 v[126:129], v[154:157], v[188:191], v[126:129]
	v_mfma_f32_16x16x32_bf16 v[126:129], v[158:161], v[198:201], v[126:129]
	v_mfma_f32_16x16x32_bf16 v[110:113], v[154:157], v[202:205], v[110:113]
	v_mfma_f32_16x16x32_bf16 v[110:113], v[158:161], v[206:209], v[110:113]
	v_mfma_f32_16x16x32_bf16 v[94:97], v[154:157], v[210:213], v[94:97]
	v_mfma_f32_16x16x32_bf16 v[94:97], v[158:161], v[214:217], v[94:97]
	v_mfma_f32_16x16x32_bf16 v[78:81], v[154:157], v[218:221], v[78:81]
	v_mfma_f32_16x16x32_bf16 v[78:81], v[158:161], v[222:225], v[78:81]
	v_mfma_f32_16x16x32_bf16 v[74:77], v[162:165], v[218:221], v[74:77]
	v_mfma_f32_16x16x32_bf16 v[74:77], v[166:169], v[222:225], v[74:77]
	v_mfma_f32_16x16x32_bf16 v[90:93], v[162:165], v[210:213], v[90:93]
	v_mfma_f32_16x16x32_bf16 v[90:93], v[166:169], v[214:217], v[90:93]
	v_mfma_f32_16x16x32_bf16 v[106:109], v[162:165], v[202:205], v[106:109]
	v_mfma_f32_16x16x32_bf16 v[106:109], v[166:169], v[206:209], v[106:109]
	v_mfma_f32_16x16x32_bf16 v[122:125], v[162:165], v[188:191], v[122:125]
	v_mfma_f32_16x16x32_bf16 v[122:125], v[166:169], v[198:201], v[122:125]
	s_setprio 0
	s_setprio 1
	v_mfma_f32_16x16x32_bf16 v[118:121], v[170:173], v[188:191], v[118:121]
	v_mfma_f32_16x16x32_bf16 v[118:121], v[174:177], v[198:201], v[118:121]
	v_mfma_f32_16x16x32_bf16 v[102:105], v[170:173], v[202:205], v[102:105]
	v_mfma_f32_16x16x32_bf16 v[102:105], v[174:177], v[206:209], v[102:105]
	v_mfma_f32_16x16x32_bf16 v[86:89], v[170:173], v[210:213], v[86:89]
	v_mfma_f32_16x16x32_bf16 v[86:89], v[174:177], v[214:217], v[86:89]
	v_mfma_f32_16x16x32_bf16 v[70:73], v[170:173], v[218:221], v[70:73]
	v_mfma_f32_16x16x32_bf16 v[70:73], v[174:177], v[222:225], v[70:73]
	v_mfma_f32_16x16x32_bf16 v[66:69], v[180:183], v[218:221], v[66:69]
	v_mfma_f32_16x16x32_bf16 v[66:69], v[184:187], v[222:225], v[66:69]
	v_mfma_f32_16x16x32_bf16 v[82:85], v[180:183], v[210:213], v[82:85]
	v_mfma_f32_16x16x32_bf16 v[82:85], v[184:187], v[214:217], v[82:85]
	v_mfma_f32_16x16x32_bf16 v[98:101], v[180:183], v[202:205], v[98:101]
	v_mfma_f32_16x16x32_bf16 v[98:101], v[184:187], v[206:209], v[98:101]
	v_mfma_f32_16x16x32_bf16 v[114:117], v[180:183], v[188:191], v[114:117]
	v_mfma_f32_16x16x32_bf16 v[114:117], v[184:187], v[198:201], v[114:117]
	s_setprio 0
	s_barrier
	s_add_i32 s71, s59, s3
	s_mov_b32 m0, s71
	ds_read_b128 v[188:191], v151 offset:16384
	ds_read_b128 v[198:201], v151 offset:17408
	ds_read_b128 v[202:205], v151 offset:18432
	ds_read_b128 v[206:209], v151 offset:19456
	ds_read_b128 v[210:213], v151 offset:20480
	ds_read_b128 v[214:217], v151 offset:21504
	ds_read_b128 v[218:221], v151 offset:22528
	ds_read_b128 v[222:225], v151 offset:23552
	global_load_lds_dwordx4 v132, s[48:49]
	s_add_i32 m0, s71, 0x2000
	s_add_u32 s72, s48, 0x4000
	v_lshl_add_u64 v[146:147], s[48:49], 0, v[136:137]
	s_addc_u32 s73, s49, 0
	s_add_i32 s71, s61, s3
	global_load_lds_dwordx4 v[146:147], off
	s_mov_b32 m0, s71
	s_nop 0
	global_load_lds_dwordx4 v132, s[72:73]
	s_add_i32 m0, s71, 0x2000
	s_nop 0
	global_load_lds_dwordx4 v136, s[72:73]
	s_waitcnt vmcnt(6)
	s_waitcnt lgkmcnt(0)
	s_barrier
	s_setprio 1
	s_waitcnt lgkmcnt(0)
	v_mfma_f32_16x16x32_bf16 v[62:65], v[154:157], v[188:191], v[62:65]
	v_mfma_f32_16x16x32_bf16 v[62:65], v[158:161], v[198:201], v[62:65]
	v_mfma_f32_16x16x32_bf16 v[46:49], v[154:157], v[202:205], v[46:49]
	v_mfma_f32_16x16x32_bf16 v[46:49], v[158:161], v[206:209], v[46:49]
	v_mfma_f32_16x16x32_bf16 v[30:33], v[154:157], v[210:213], v[30:33]
	v_mfma_f32_16x16x32_bf16 v[30:33], v[158:161], v[214:217], v[30:33]
	v_mfma_f32_16x16x32_bf16 v[14:17], v[154:157], v[218:221], v[14:17]
	v_mfma_f32_16x16x32_bf16 v[14:17], v[158:161], v[222:225], v[14:17]
	v_mfma_f32_16x16x32_bf16 v[10:13], v[162:165], v[218:221], v[10:13]
	v_mfma_f32_16x16x32_bf16 v[10:13], v[166:169], v[222:225], v[10:13]
	v_mfma_f32_16x16x32_bf16 v[26:29], v[162:165], v[210:213], v[26:29]
	v_mfma_f32_16x16x32_bf16 v[26:29], v[166:169], v[214:217], v[26:29]
	v_mfma_f32_16x16x32_bf16 v[42:45], v[162:165], v[202:205], v[42:45]
	v_mfma_f32_16x16x32_bf16 v[42:45], v[166:169], v[206:209], v[42:45]
	v_mfma_f32_16x16x32_bf16 v[58:61], v[162:165], v[188:191], v[58:61]
	v_mfma_f32_16x16x32_bf16 v[58:61], v[166:169], v[198:201], v[58:61]
	s_setprio 0
	s_setprio 1
	v_mfma_f32_16x16x32_bf16 v[54:57], v[170:173], v[188:191], v[54:57]
	v_mfma_f32_16x16x32_bf16 v[54:57], v[174:177], v[198:201], v[54:57]
	v_mfma_f32_16x16x32_bf16 v[38:41], v[170:173], v[202:205], v[38:41]
	v_mfma_f32_16x16x32_bf16 v[38:41], v[174:177], v[206:209], v[38:41]
	v_mfma_f32_16x16x32_bf16 v[22:25], v[170:173], v[210:213], v[22:25]
	v_mfma_f32_16x16x32_bf16 v[22:25], v[174:177], v[214:217], v[22:25]
	v_mfma_f32_16x16x32_bf16 v[6:9], v[170:173], v[218:221], v[6:9]
	v_mfma_f32_16x16x32_bf16 v[6:9], v[174:177], v[222:225], v[6:9]
	v_mfma_f32_16x16x32_bf16 v[2:5], v[180:183], v[218:221], v[2:5]
	v_mfma_f32_16x16x32_bf16 v[2:5], v[184:187], v[222:225], v[2:5]
	v_mfma_f32_16x16x32_bf16 v[18:21], v[180:183], v[210:213], v[18:21]
	v_mfma_f32_16x16x32_bf16 v[18:21], v[184:187], v[214:217], v[18:21]
	v_mfma_f32_16x16x32_bf16 v[34:37], v[180:183], v[202:205], v[34:37]
	v_mfma_f32_16x16x32_bf16 v[34:37], v[184:187], v[206:209], v[34:37]
	v_mfma_f32_16x16x32_bf16 v[50:53], v[180:183], v[188:191], v[50:53]
	v_mfma_f32_16x16x32_bf16 v[50:53], v[184:187], v[198:201], v[50:53]
	s_setprio 0
	s_barrier
; #define PG8_STAGE(bufoff, gbase, voff) do { _Pragma("unroll") for (int _i = 0; _i < 2; ++_i) \
;         __builtin_amdgcn_global_load_lds((const unsigned*)((const char*)(gbase) + (voff)[_i]), (PG8_LAS unsigned*)(lds + (bufoff) + ldsw + _i * 8192), 16, 0, 0); } while (0)
; #define PG8_LDA(dst, b, h) do { _Pragma("unroll") for (int m = 0; m < 4; ++m) _Pragma("unroll") for (int k = 0; k < 2; ++k) dst[m][k] = *(const PG8_LAS bf16x8*)(lds + PG8_SA(b, h) + aoff + m * 2048 + k * 1024); } while (0)
; #define PG8_LDB(dst, b, h) do { _Pragma("unroll") for (int n = 0; n < 2; ++n) _Pragma("unroll") for (int k = 0; k < 2; ++k) dst[n][k] = *(const PG8_LAS bf16x8*)(lds + PG8_SB(b, h) + boff + n * 2048 + k * 1024); } while (0)
; #define PG8_MMA(ai, bj, At, Bt) do { __builtin_amdgcn_s_setprio(1); _Pragma("unroll") for (int m = 0; m < 4; ++m) _Pragma("unroll") for (int n = 0; n < 2; ++n) _Pragma("unroll") for (int k = 0; k < 2; ++k) \
;         acc[ai][bj][m][n] = __builtin_amdgcn_mfma_f32_16x16x32_bf16(Bt[n][k], At[m][k], acc[ai][bj][m][n], 0, 0, 0); __builtin_amdgcn_s_setprio(0); } while (0)
; #define PG8_WAIT_V(n) asm volatile("s_waitcnt vmcnt(" #n ")" ::: "memory")
; #define PG8_WAIT_L(n) asm volatile("s_waitcnt lgkmcnt(" #n ")" ::: "memory")
; #define PG8_BAR __builtin_amdgcn_s_barrier()
; #define PG8_SCHED __builtin_amdgcn_sched_barrier(0)
; template <class Epi, class Sched, bool ALIGN_EPI = false, bool SP2 = false>
; __device__ __forceinline__ void gemm_phase(PG8_LAS unsigned char* lds, const Gemm g, const Sched& S, const Epi& E) {
;     ...
;         for (; t < tend; t += 2) {
;     ...
;             PG8_LDB(B0, 1, 0); PG8_LDB(B1, 1, 1); PG8_SCHED; PG8_LDA(At, 1, 0); PG8_STAGE(PG8_SA(0, 1), a2 + hstep, voffA);
;             PG8_WAIT_V(8); PG8_WAIT_L(0); PG8_BAR; PG8_MMA(0, 0, At, B0); PG8_MMA(0, 1, At, B1); PG8_BAR; PG8_SCHED;
;             PG8_LDA(At, 1, 1); PG8_STAGE(PG8_SB(1, 0), b3, voffB); PG8_STAGE(PG8_SB(1, 1), b3 + hstep, voffB); PG8_STAGE(PG8_SA(1, 0), a3, voffA);
;             PG8_WAIT_V(8); PG8_WAIT_L(0); PG8_BAR; PG8_MMA(1, 0, At, B0); PG8_MMA(1, 1, At, B1); PG8_BAR; PG8_SCHED;
	s_add_i32 s71, 0, 0x18000
	v_add_u32_e32 v146, s71, v1
	s_add_i32 s72, 0, 0x1c000
	ds_read_b128 v[154:157], v146
	ds_read_b128 v[158:161], v146 offset:1024
	ds_read_b128 v[162:165], v146 offset:2048
	ds_read_b128 v[166:169], v146 offset:3072
	v_add_u32_e32 v146, s72, v1
	ds_read_b128 v[170:173], v146
	ds_read_b128 v[174:177], v146 offset:1024
	ds_read_b128 v[180:183], v146 offset:2048
	ds_read_b128 v[184:187], v146 offset:3072
	s_mov_b32 m0, s26
	s_nop 0
	global_load_lds_dwordx4 v130, s[50:51]
	s_mov_b32 m0, s27
	s_nop 0
	global_load_lds_dwordx4 v134, s[50:51]
	s_add_u32 s50, s50, 0x4000
	s_addc_u32 s51, s51, 0
	s_mov_b32 m0, s28
	ds_read_b128 v[188:191], v151 offset:32768
	ds_read_b128 v[198:201], v151 offset:33792
	ds_read_b128 v[202:205], v151 offset:34816
	ds_read_b128 v[206:209], v151 offset:35840
	ds_read_b128 v[210:213], v151 offset:36864
	ds_read_b128 v[214:217], v151 offset:37888
	ds_read_b128 v[218:221], v151 offset:38912
	ds_read_b128 v[222:225], v151 offset:39936
	global_load_lds_dwordx4 v130, s[50:51]
	s_mov_b32 m0, s29
	s_nop 0
	global_load_lds_dwordx4 v134, s[50:51]
	s_waitcnt vmcnt(8)
	s_waitcnt lgkmcnt(0)
	s_barrier
	s_setprio 1
	s_waitcnt lgkmcnt(0)
	v_mfma_f32_16x16x32_bf16 v[126:129], v[154:157], v[188:191], v[126:129]
	v_mfma_f32_16x16x32_bf16 v[126:129], v[158:161], v[198:201], v[126:129]
	v_mfma_f32_16x16x32_bf16 v[110:113], v[154:157], v[202:205], v[110:113]
	v_mfma_f32_16x16x32_bf16 v[110:113], v[158:161], v[206:209], v[110:113]
	v_mfma_f32_16x16x32_bf16 v[94:97], v[154:157], v[210:213], v[94:97]
	v_mfma_f32_16x16x32_bf16 v[94:97], v[158:161], v[214:217], v[94:97]
	v_mfma_f32_16x16x32_bf16 v[78:81], v[154:157], v[218:221], v[78:81]
	v_mfma_f32_16x16x32_bf16 v[78:81], v[158:161], v[222:225], v[78:81]
	v_mfma_f32_16x16x32_bf16 v[74:77], v[162:165], v[218:221], v[74:77]
	v_mfma_f32_16x16x32_bf16 v[74:77], v[166:169], v[222:225], v[74:77]
	v_mfma_f32_16x16x32_bf16 v[90:93], v[162:165], v[210:213], v[90:93]
	v_mfma_f32_16x16x32_bf16 v[90:93], v[166:169], v[214:217], v[90:93]
	v_mfma_f32_16x16x32_bf16 v[106:109], v[162:165], v[202:205], v[106:109]
	v_mfma_f32_16x16x32_bf16 v[106:109], v[166:169], v[206:209], v[106:109]
	v_mfma_f32_16x16x32_bf16 v[122:125], v[162:165], v[188:191], v[122:125]
	v_mfma_f32_16x16x32_bf16 v[122:125], v[166:169], v[198:201], v[122:125]
	s_setprio 0
	s_setprio 1
	v_mfma_f32_16x16x32_bf16 v[118:121], v[170:173], v[188:191], v[118:121]
	v_mfma_f32_16x16x32_bf16 v[118:121], v[174:177], v[198:201], v[118:121]
	v_mfma_f32_16x16x32_bf16 v[102:105], v[170:173], v[202:205], v[102:105]
	v_mfma_f32_16x16x32_bf16 v[102:105], v[174:177], v[206:209], v[102:105]
	v_mfma_f32_16x16x32_bf16 v[86:89], v[170:173], v[210:213], v[86:89]
	v_mfma_f32_16x16x32_bf16 v[86:89], v[174:177], v[214:217], v[86:89]
	v_mfma_f32_16x16x32_bf16 v[70:73], v[170:173], v[218:221], v[70:73]
	v_mfma_f32_16x16x32_bf16 v[70:73], v[174:177], v[222:225], v[70:73]
	v_mfma_f32_16x16x32_bf16 v[66:69], v[180:183], v[218:221], v[66:69]
	v_mfma_f32_16x16x32_bf16 v[66:69], v[184:187], v[222:225], v[66:69]
	v_mfma_f32_16x16x32_bf16 v[82:85], v[180:183], v[210:213], v[82:85]
	v_mfma_f32_16x16x32_bf16 v[82:85], v[184:187], v[214:217], v[82:85]
	v_mfma_f32_16x16x32_bf16 v[98:101], v[180:183], v[202:205], v[98:101]
	v_mfma_f32_16x16x32_bf16 v[98:101], v[184:187], v[206:209], v[98:101]
	v_mfma_f32_16x16x32_bf16 v[114:117], v[180:183], v[188:191], v[114:117]
	v_mfma_f32_16x16x32_bf16 v[114:117], v[184:187], v[198:201], v[114:117]
	s_setprio 0
	s_barrier
	s_add_u32 s50, s48, 0x8000
	s_addc_u32 s51, s49, 0
	s_add_i32 s71, s71, s3
	s_mov_b32 m0, s71
	ds_read_b128 v[188:191], v151 offset:49152
	ds_read_b128 v[198:201], v151 offset:50176
	ds_read_b128 v[202:205], v151 offset:51200
	ds_read_b128 v[206:209], v151 offset:52224
	ds_read_b128 v[210:213], v151 offset:53248
	ds_read_b128 v[214:217], v151 offset:54272
	ds_read_b128 v[218:221], v151 offset:55296
	ds_read_b128 v[222:225], v151 offset:56320
	global_load_lds_dwordx4 v132, s[50:51]
	s_add_i32 m0, s71, 0x2000
	s_add_u32 s48, s48, 0xc000
	v_lshl_add_u64 v[146:147], s[50:51], 0, v[136:137]
	s_addc_u32 s49, s49, 0
	s_add_i32 s50, s72, s3
	global_load_lds_dwordx4 v[146:147], off
	s_mov_b32 m0, s50
	s_nop 0
	global_load_lds_dwordx4 v132, s[48:49]
	s_add_i32 m0, s50, 0x2000
	s_nop 0
	global_load_lds_dwordx4 v136, s[48:49]
	s_waitcnt vmcnt(6)
	s_waitcnt lgkmcnt(0)
	s_barrier
	s_setprio 1
	s_waitcnt lgkmcnt(0)
	v_mfma_f32_16x16x32_bf16 v[62:65], v[154:157], v[188:191], v[62:65]
	v_mfma_f32_16x16x32_bf16 v[62:65], v[158:161], v[198:201], v[62:65]
	v_mfma_f32_16x16x32_bf16 v[46:49], v[154:157], v[202:205], v[46:49]
	v_mfma_f32_16x16x32_bf16 v[46:49], v[158:161], v[206:209], v[46:49]
	v_mfma_f32_16x16x32_bf16 v[30:33], v[154:157], v[210:213], v[30:33]
	v_mfma_f32_16x16x32_bf16 v[30:33], v[158:161], v[214:217], v[30:33]
	v_mfma_f32_16x16x32_bf16 v[14:17], v[154:157], v[218:221], v[14:17]
	v_mfma_f32_16x16x32_bf16 v[14:17], v[158:161], v[222:225], v[14:17]
	v_mfma_f32_16x16x32_bf16 v[10:13], v[162:165], v[218:221], v[10:13]
	v_mfma_f32_16x16x32_bf16 v[10:13], v[166:169], v[222:225], v[10:13]
	v_mfma_f32_16x16x32_bf16 v[26:29], v[162:165], v[210:213], v[26:29]
	v_mfma_f32_16x16x32_bf16 v[26:29], v[166:169], v[214:217], v[26:29]
	v_mfma_f32_16x16x32_bf16 v[42:45], v[162:165], v[202:205], v[42:45]
	v_mfma_f32_16x16x32_bf16 v[42:45], v[166:169], v[206:209], v[42:45]
	v_mfma_f32_16x16x32_bf16 v[58:61], v[162:165], v[188:191], v[58:61]
	v_mfma_f32_16x16x32_bf16 v[58:61], v[166:169], v[198:201], v[58:61]
	s_setprio 0
	s_setprio 1
	v_mfma_f32_16x16x32_bf16 v[54:57], v[170:173], v[188:191], v[54:57]
	v_mfma_f32_16x16x32_bf16 v[54:57], v[174:177], v[198:201], v[54:57]
	v_mfma_f32_16x16x32_bf16 v[38:41], v[170:173], v[202:205], v[38:41]
	v_mfma_f32_16x16x32_bf16 v[38:41], v[174:177], v[206:209], v[38:41]
	v_mfma_f32_16x16x32_bf16 v[22:25], v[170:173], v[210:213], v[22:25]
	v_mfma_f32_16x16x32_bf16 v[22:25], v[174:177], v[214:217], v[22:25]
	v_mfma_f32_16x16x32_bf16 v[6:9], v[170:173], v[218:221], v[6:9]
	v_mfma_f32_16x16x32_bf16 v[6:9], v[174:177], v[222:225], v[6:9]
	v_mfma_f32_16x16x32_bf16 v[2:5], v[180:183], v[218:221], v[2:5]
	v_mfma_f32_16x16x32_bf16 v[2:5], v[184:187], v[222:225], v[2:5]
	v_mfma_f32_16x16x32_bf16 v[18:21], v[180:183], v[210:213], v[18:21]
	v_mfma_f32_16x16x32_bf16 v[18:21], v[184:187], v[214:217], v[18:21]
	v_mfma_f32_16x16x32_bf16 v[34:37], v[180:183], v[202:205], v[34:37]
	v_mfma_f32_16x16x32_bf16 v[34:37], v[184:187], v[206:209], v[34:37]
	v_mfma_f32_16x16x32_bf16 v[50:53], v[180:183], v[188:191], v[50:53]
	v_mfma_f32_16x16x32_bf16 v[50:53], v[184:187], v[198:201], v[50:53]
	s_setprio 0
	s_barrier
	s_add_i32 s70, s70, 2
	s_add_u32 s44, s44, 0x10000
	s_addc_u32 s45, s45, 0
	s_add_u32 s68, s68, 0x10000
	s_addc_u32 s69, s69, 0
	s_cmp_gt_u32 s70, 61
	s_cbranch_scc0 .LBB0_757
	s_and_b64 vcc, exec, s[12:13]
	s_cbranch_vccz .LBB0_760
	s_barrier

; #define PG8_STAGE(bufoff, gbase, voff) do { _Pragma("unroll") for (int _i = 0; _i < 2; ++_i) \
;         __builtin_amdgcn_global_load_lds((const unsigned*)((const char*)(gbase) + (voff)[_i]), (PG8_LAS unsigned*)(lds + (bufoff) + ldsw + _i * 8192), 16, 0, 0); } while (0)
; #define PG8_LDA(dst, b, h) do { _Pragma("unroll") for (int m = 0; m < 4; ++m) _Pragma("unroll") for (int k = 0; k < 2; ++k) dst[m][k] = *(const PG8_LAS bf16x8*)(lds + PG8_SA(b, h) + aoff + m * 2048 + k * 1024); } while (0)
; #define PG8_LDB(dst, b, h) do { _Pragma("unroll") for (int n = 0; n < 2; ++n) _Pragma("unroll") for (int k = 0; k < 2; ++k) dst[n][k] = *(const PG8_LAS bf16x8*)(lds + PG8_SB(b, h) + boff + n * 2048 + k * 1024); } while (0)
; #define PG8_MMA(ai, bj, At, Bt) do { __builtin_amdgcn_s_setprio(1); _Pragma("unroll") for (int m = 0; m < 4; ++m) _Pragma("unroll") for (int n = 0; n < 2; ++n) _Pragma("unroll") for (int k = 0; k < 2; ++k) \
;         acc[ai][bj][m][n] = __builtin_amdgcn_mfma_f32_16x16x32_bf16(Bt[n][k], At[m][k], acc[ai][bj][m][n], 0, 0, 0); __builtin_amdgcn_s_setprio(0); } while (0)
; #define PG8_WAIT_V(n) asm volatile("s_waitcnt vmcnt(" #n ")" ::: "memory")
; #define PG8_WAIT_L(n) asm volatile("s_waitcnt lgkmcnt(" #n ")" ::: "memory")
; template <class Epi, class Sched, bool ALIGN_EPI = false, bool SP2 = false>
; __device__ __forceinline__ void gemm_phase(PG8_LAS unsigned char* lds, const Gemm g, const Sched& S, const Epi& E) {
;     ...
;             const bool last = (t == nt - 2);
;             const char* a1 = cA + (size_t)(t + 1) * kstep;
;             const char* a2 = last ? nA : cA + (size_t)(t + 2) * kstep; const char* b2 = last ? nB : cB + (size_t)(t + 2) * kstep;
;             const char* a3 = a2 + kstep; const char* b3 = b2 + kstep;
;             if (last && has_next) S.a_ready(nxt);
;             if constexpr (SP2) {
;             PG8_LDB(B0, 0, 0); PG8_LDB(B1, 0, 1); PG8_SCHED; PG8_LDA(At, 0, 0); PG8_STAGE(PG8_SA(1, 1), a1 + hstep, voffA);
;             PG8_WAIT_V(8); PG8_WAIT_L(0); PG8_BAR; PG8_MMA(0, 0, At, B0); PG8_MMA(0, 1, At, B1); PG8_BAR; PG8_SCHED;
;             PG8_LDA(At, 0, 1); PG8_STAGE(PG8_SB(0, 0), b2, voffB); PG8_STAGE(PG8_SB(0, 1), b2 + hstep, voffB); PG8_STAGE(PG8_SA(0, 0), a2, voffA);
;             PG8_WAIT_V(8); PG8_WAIT_L(0); PG8_BAR; PG8_MMA(1, 0, At, B0); PG8_MMA(1, 1, At, B1); PG8_BAR; PG8_SCHED;
.LBB0_840:
	ds_read_b128 v[148:151], v153
	ds_read_b128 v[158:161], v153 offset:1024
	ds_read_b128 v[162:165], v153 offset:2048
	ds_read_b128 v[166:169], v153 offset:3072
	ds_read_b128 v[170:173], v154
	ds_read_b128 v[174:177], v154 offset:1024
	ds_read_b128 v[180:183], v154 offset:2048
	ds_read_b128 v[184:187], v154 offset:3072
	s_add_u32 s42, s40, 0x4000
	s_addc_u32 s43, s41, 0
	s_cmp_eq_u32 s69, 60
	s_cselect_b32 s46, s65, s42
	s_cselect_b32 s47, s23, s43
	s_cselect_b32 s44, s66, s67
	s_cselect_b32 s45, s17, s68
	s_add_u32 s42, s46, 0x8000
	s_addc_u32 s43, s47, 0
	s_sub_u32 s42, s40, 0x4000
	s_subb_u32 s43, s41, 0
	s_mov_b32 m0, s50
	s_nop 0
	global_load_lds_dwordx4 v130, s[42:43]
	s_mov_b32 m0, s51
	s_nop 0
	global_load_lds_dwordx4 v134, s[42:43]
	s_add_i32 m0, s28, 0xc000
	ds_read_b128 v[188:191], v155
	ds_read_b128 v[198:201], v155 offset:1024
	ds_read_b128 v[202:205], v155 offset:2048
	ds_read_b128 v[206:209], v155 offset:3072
	ds_read_b128 v[210:213], v155 offset:4096
	ds_read_b128 v[214:217], v155 offset:5120
	ds_read_b128 v[218:221], v155 offset:6144
	ds_read_b128 v[222:225], v155 offset:7168
	global_load_lds_dwordx4 v140, s[40:41]
	s_add_i32 m0, s28, 0xe000
	s_nop 0
	global_load_lds_dwordx4 v142, s[40:41]
	s_waitcnt vmcnt(8)
	s_waitcnt lgkmcnt(0)
	s_barrier
	s_setprio 1
	s_waitcnt lgkmcnt(0)
	v_mfma_f32_16x16x32_bf16 v[126:129], v[148:151], v[188:191], v[126:129]
	v_mfma_f32_16x16x32_bf16 v[126:129], v[158:161], v[198:201], v[126:129]
	v_mfma_f32_16x16x32_bf16 v[110:113], v[148:151], v[202:205], v[110:113]
	v_mfma_f32_16x16x32_bf16 v[110:113], v[158:161], v[206:209], v[110:113]
	v_mfma_f32_16x16x32_bf16 v[94:97], v[148:151], v[210:213], v[94:97]
	v_mfma_f32_16x16x32_bf16 v[94:97], v[158:161], v[214:217], v[94:97]
	v_mfma_f32_16x16x32_bf16 v[78:81], v[148:151], v[218:221], v[78:81]
	v_mfma_f32_16x16x32_bf16 v[78:81], v[158:161], v[222:225], v[78:81]
	v_mfma_f32_16x16x32_bf16 v[74:77], v[162:165], v[218:221], v[74:77]
	v_mfma_f32_16x16x32_bf16 v[74:77], v[166:169], v[222:225], v[74:77]
	v_mfma_f32_16x16x32_bf16 v[90:93], v[162:165], v[210:213], v[90:93]
	v_mfma_f32_16x16x32_bf16 v[90:93], v[166:169], v[214:217], v[90:93]
	v_mfma_f32_16x16x32_bf16 v[106:109], v[162:165], v[202:205], v[106:109]
	v_mfma_f32_16x16x32_bf16 v[106:109], v[166:169], v[206:209], v[106:109]
	v_mfma_f32_16x16x32_bf16 v[122:125], v[162:165], v[188:191], v[122:125]
	v_mfma_f32_16x16x32_bf16 v[122:125], v[166:169], v[198:201], v[122:125]
	s_setprio 0
	s_setprio 1
	v_mfma_f32_16x16x32_bf16 v[118:121], v[170:173], v[188:191], v[118:121]
	v_mfma_f32_16x16x32_bf16 v[118:121], v[174:177], v[198:201], v[118:121]
	v_mfma_f32_16x16x32_bf16 v[102:105], v[170:173], v[202:205], v[102:105]
	v_mfma_f32_16x16x32_bf16 v[102:105], v[174:177], v[206:209], v[102:105]
	v_mfma_f32_16x16x32_bf16 v[86:89], v[170:173], v[210:213], v[86:89]
	v_mfma_f32_16x16x32_bf16 v[86:89], v[174:177], v[214:217], v[86:89]
	v_mfma_f32_16x16x32_bf16 v[70:73], v[170:173], v[218:221], v[70:73]
	v_mfma_f32_16x16x32_bf16 v[70:73], v[174:177], v[222:225], v[70:73]
	v_mfma_f32_16x16x32_bf16 v[66:69], v[180:183], v[218:221], v[66:69]
	v_mfma_f32_16x16x32_bf16 v[66:69], v[184:187], v[222:225], v[66:69]
	v_mfma_f32_16x16x32_bf16 v[82:85], v[180:183], v[210:213], v[82:85]
	v_mfma_f32_16x16x32_bf16 v[82:85], v[184:187], v[214:217], v[82:85]
	v_mfma_f32_16x16x32_bf16 v[98:101], v[180:183], v[202:205], v[98:101]
	v_mfma_f32_16x16x32_bf16 v[98:101], v[184:187], v[206:209], v[98:101]
	v_mfma_f32_16x16x32_bf16 v[114:117], v[180:183], v[188:191], v[114:117]
	v_mfma_f32_16x16x32_bf16 v[114:117], v[184:187], v[198:201], v[114:117]
	s_setprio 0
	s_barrier
	s_add_i32 s70, s56, s3
	s_mov_b32 m0, s70
	ds_read_b128 v[188:191], v155 offset:16384
	ds_read_b128 v[198:201], v155 offset:17408
	ds_read_b128 v[202:205], v155 offset:18432
	ds_read_b128 v[206:209], v155 offset:19456
	ds_read_b128 v[210:213], v155 offset:20480
	ds_read_b128 v[214:217], v155 offset:21504
	ds_read_b128 v[218:221], v155 offset:22528
	ds_read_b128 v[222:225], v155 offset:23552
	global_load_lds_dwordx4 v132, s[44:45]
	s_add_i32 m0, s70, 0x2000
	s_add_u32 s70, s44, 0x4000
	v_lshl_add_u64 v[226:227], s[44:45], 0, v[136:137]
	s_addc_u32 s71, s45, 0
	s_add_i32 s72, s57, s3
	global_load_lds_dwordx4 v[226:227], off
	s_mov_b32 m0, s72
	s_nop 0
	global_load_lds_dwordx4 v132, s[70:71]
	s_add_i32 m0, s72, 0x2000
	s_nop 0
	global_load_lds_dwordx4 v136, s[70:71]
	s_waitcnt vmcnt(6)
	s_waitcnt lgkmcnt(0)
	s_barrier
	s_setprio 1
	s_waitcnt lgkmcnt(0)
	v_mfma_f32_16x16x32_bf16 v[62:65], v[148:151], v[188:191], v[62:65]
	v_mfma_f32_16x16x32_bf16 v[62:65], v[158:161], v[198:201], v[62:65]
	v_mfma_f32_16x16x32_bf16 v[46:49], v[148:151], v[202:205], v[46:49]
	v_mfma_f32_16x16x32_bf16 v[46:49], v[158:161], v[206:209], v[46:49]
	v_mfma_f32_16x16x32_bf16 v[30:33], v[148:151], v[210:213], v[30:33]
	v_mfma_f32_16x16x32_bf16 v[30:33], v[158:161], v[214:217], v[30:33]
	v_mfma_f32_16x16x32_bf16 v[14:17], v[148:151], v[218:221], v[14:17]
	v_mfma_f32_16x16x32_bf16 v[14:17], v[158:161], v[222:225], v[14:17]
	v_mfma_f32_16x16x32_bf16 v[10:13], v[162:165], v[218:221], v[10:13]
	v_mfma_f32_16x16x32_bf16 v[10:13], v[166:169], v[222:225], v[10:13]
	v_mfma_f32_16x16x32_bf16 v[26:29], v[162:165], v[210:213], v[26:29]
	v_mfma_f32_16x16x32_bf16 v[26:29], v[166:169], v[214:217], v[26:29]
	v_mfma_f32_16x16x32_bf16 v[42:45], v[162:165], v[202:205], v[42:45]
	v_mfma_f32_16x16x32_bf16 v[42:45], v[166:169], v[206:209], v[42:45]
	v_mfma_f32_16x16x32_bf16 v[58:61], v[162:165], v[188:191], v[58:61]
	v_mfma_f32_16x16x32_bf16 v[58:61], v[166:169], v[198:201], v[58:61]
	s_setprio 0
	s_setprio 1
	v_mfma_f32_16x16x32_bf16 v[54:57], v[170:173], v[188:191], v[54:57]
	v_mfma_f32_16x16x32_bf16 v[54:57], v[174:177], v[198:201], v[54:57]
	v_mfma_f32_16x16x32_bf16 v[38:41], v[170:173], v[202:205], v[38:41]
	v_mfma_f32_16x16x32_bf16 v[38:41], v[174:177], v[206:209], v[38:41]
	v_mfma_f32_16x16x32_bf16 v[22:25], v[170:173], v[210:213], v[22:25]
	v_mfma_f32_16x16x32_bf16 v[22:25], v[174:177], v[214:217], v[22:25]
	v_mfma_f32_16x16x32_bf16 v[6:9], v[170:173], v[218:221], v[6:9]
	v_mfma_f32_16x16x32_bf16 v[6:9], v[174:177], v[222:225], v[6:9]
	v_mfma_f32_16x16x32_bf16 v[2:5], v[180:183], v[218:221], v[2:5]
	v_mfma_f32_16x16x32_bf16 v[2:5], v[184:187], v[222:225], v[2:5]
	v_mfma_f32_16x16x32_bf16 v[18:21], v[180:183], v[210:213], v[18:21]
	v_mfma_f32_16x16x32_bf16 v[18:21], v[184:187], v[214:217], v[18:21]
	v_mfma_f32_16x16x32_bf16 v[34:37], v[180:183], v[202:205], v[34:37]
	v_mfma_f32_16x16x32_bf16 v[34:37], v[184:187], v[206:209], v[34:37]
	v_mfma_f32_16x16x32_bf16 v[50:53], v[180:183], v[188:191], v[50:53]
	v_mfma_f32_16x16x32_bf16 v[50:53], v[184:187], v[198:201], v[50:53]
	s_setprio 0
	s_barrier
; #define PG8_STAGE(bufoff, gbase, voff) do { _Pragma("unroll") for (int _i = 0; _i < 2; ++_i) \
;         __builtin_amdgcn_global_load_lds((const unsigned*)((const char*)(gbase) + (voff)[_i]), (PG8_LAS unsigned*)(lds + (bufoff) + ldsw + _i * 8192), 16, 0, 0); } while (0)
; #define PG8_LDA(dst, b, h) do { _Pragma("unroll") for (int m = 0; m < 4; ++m) _Pragma("unroll") for (int k = 0; k < 2; ++k) dst[m][k] = *(const PG8_LAS bf16x8*)(lds + PG8_SA(b, h) + aoff + m * 2048 + k * 1024); } while (0)
; #define PG8_LDB(dst, b, h) do { _Pragma("unroll") for (int n = 0; n < 2; ++n) _Pragma("unroll") for (int k = 0; k < 2; ++k) dst[n][k] = *(const PG8_LAS bf16x8*)(lds + PG8_SB(b, h) + boff + n * 2048 + k * 1024); } while (0)
; #define PG8_MMA(ai, bj, At, Bt) do { __builtin_amdgcn_s_setprio(1); _Pragma("unroll") for (int m = 0; m < 4; ++m) _Pragma("unroll") for (int n = 0; n < 2; ++n) _Pragma("unroll") for (int k = 0; k < 2; ++k) \
;         acc[ai][bj][m][n] = __builtin_amdgcn_mfma_f32_16x16x32_bf16(Bt[n][k], At[m][k], acc[ai][bj][m][n], 0, 0, 0); __builtin_amdgcn_s_setprio(0); } while (0)
; #define PG8_WAIT_V(n) asm volatile("s_waitcnt vmcnt(" #n ")" ::: "memory")
; #define PG8_WAIT_L(n) asm volatile("s_waitcnt lgkmcnt(" #n ")" ::: "memory")
; #define PG8_BAR __builtin_amdgcn_s_barrier()
; #define PG8_SCHED __builtin_amdgcn_sched_barrier(0)
; template <class Epi, class Sched, bool ALIGN_EPI = false, bool SP2 = false>
; __device__ __forceinline__ void gemm_phase(PG8_LAS unsigned char* lds, const Gemm g, const Sched& S, const Epi& E) {
;     ...
;         for (; t < tend; t += 2) {
;     ...
;             PG8_LDB(B0, 1, 0); PG8_LDB(B1, 1, 1); PG8_SCHED; PG8_LDA(At, 1, 0); PG8_STAGE(PG8_SA(0, 1), a2 + hstep, voffA);
;             PG8_WAIT_V(8); PG8_WAIT_L(0); PG8_BAR; PG8_MMA(0, 0, At, B0); PG8_MMA(0, 1, At, B1); PG8_BAR; PG8_SCHED;
;             PG8_LDA(At, 1, 1); PG8_STAGE(PG8_SB(1, 0), b3, voffB); PG8_STAGE(PG8_SB(1, 1), b3 + hstep, voffB); PG8_STAGE(PG8_SA(1, 0), a3, voffA);
;             PG8_WAIT_V(8); PG8_WAIT_L(0); PG8_BAR; PG8_MMA(1, 0, At, B0); PG8_MMA(1, 1, At, B1); PG8_BAR; PG8_SCHED;
	s_add_i32 s70, 0, 0x18000
	v_add_u32_e32 v138, s70, v1
	s_add_i32 s71, 0, 0x1c000
	ds_read_b128 v[148:151], v138
	ds_read_b128 v[158:161], v138 offset:1024
	ds_read_b128 v[162:165], v138 offset:2048
	ds_read_b128 v[166:169], v138 offset:3072
	v_add_u32_e32 v138, s71, v1
	ds_read_b128 v[170:173], v138
	ds_read_b128 v[174:177], v138 offset:1024
	ds_read_b128 v[180:183], v138 offset:2048
	ds_read_b128 v[184:187], v138 offset:3072
	s_mov_b32 m0, s28
	s_nop 0
	global_load_lds_dwordx4 v130, s[46:47]
	s_mov_b32 m0, s29
	s_nop 0
	global_load_lds_dwordx4 v134, s[46:47]
	s_add_u32 s46, s46, 0x4000
	s_addc_u32 s47, s47, 0
	s_mov_b32 m0, s30
	ds_read_b128 v[188:191], v155 offset:32768
	ds_read_b128 v[198:201], v155 offset:33792
	ds_read_b128 v[202:205], v155 offset:34816
	ds_read_b128 v[206:209], v155 offset:35840
	ds_read_b128 v[210:213], v155 offset:36864
	ds_read_b128 v[214:217], v155 offset:37888
	ds_read_b128 v[218:221], v155 offset:38912
	ds_read_b128 v[222:225], v155 offset:39936
	global_load_lds_dwordx4 v130, s[46:47]
	s_mov_b32 m0, s31
	s_nop 0
	global_load_lds_dwordx4 v134, s[46:47]
	s_waitcnt vmcnt(8)
	s_waitcnt lgkmcnt(0)
	s_barrier
	s_setprio 1
	s_waitcnt lgkmcnt(0)
	v_mfma_f32_16x16x32_bf16 v[126:129], v[148:151], v[188:191], v[126:129]
	v_mfma_f32_16x16x32_bf16 v[126:129], v[158:161], v[198:201], v[126:129]
	v_mfma_f32_16x16x32_bf16 v[110:113], v[148:151], v[202:205], v[110:113]
	v_mfma_f32_16x16x32_bf16 v[110:113], v[158:161], v[206:209], v[110:113]
	v_mfma_f32_16x16x32_bf16 v[94:97], v[148:151], v[210:213], v[94:97]
	v_mfma_f32_16x16x32_bf16 v[94:97], v[158:161], v[214:217], v[94:97]
	v_mfma_f32_16x16x32_bf16 v[78:81], v[148:151], v[218:221], v[78:81]
	v_mfma_f32_16x16x32_bf16 v[78:81], v[158:161], v[222:225], v[78:81]
	v_mfma_f32_16x16x32_bf16 v[74:77], v[162:165], v[218:221], v[74:77]
	v_mfma_f32_16x16x32_bf16 v[74:77], v[166:169], v[222:225], v[74:77]
	v_mfma_f32_16x16x32_bf16 v[90:93], v[162:165], v[210:213], v[90:93]
	v_mfma_f32_16x16x32_bf16 v[90:93], v[166:169], v[214:217], v[90:93]
	v_mfma_f32_16x16x32_bf16 v[106:109], v[162:165], v[202:205], v[106:109]
	v_mfma_f32_16x16x32_bf16 v[106:109], v[166:169], v[206:209], v[106:109]
	v_mfma_f32_16x16x32_bf16 v[122:125], v[162:165], v[188:191], v[122:125]
	v_mfma_f32_16x16x32_bf16 v[122:125], v[166:169], v[198:201], v[122:125]
	s_setprio 0
	s_setprio 1
	v_mfma_f32_16x16x32_bf16 v[118:121], v[170:173], v[188:191], v[118:121]
	v_mfma_f32_16x16x32_bf16 v[118:121], v[174:177], v[198:201], v[118:121]
	v_mfma_f32_16x16x32_bf16 v[102:105], v[170:173], v[202:205], v[102:105]
	v_mfma_f32_16x16x32_bf16 v[102:105], v[174:177], v[206:209], v[102:105]
	v_mfma_f32_16x16x32_bf16 v[86:89], v[170:173], v[210:213], v[86:89]
	v_mfma_f32_16x16x32_bf16 v[86:89], v[174:177], v[214:217], v[86:89]
	v_mfma_f32_16x16x32_bf16 v[70:73], v[170:173], v[218:221], v[70:73]
	v_mfma_f32_16x16x32_bf16 v[70:73], v[174:177], v[222:225], v[70:73]
	v_mfma_f32_16x16x32_bf16 v[66:69], v[180:183], v[218:221], v[66:69]
	v_mfma_f32_16x16x32_bf16 v[66:69], v[184:187], v[222:225], v[66:69]
	v_mfma_f32_16x16x32_bf16 v[82:85], v[180:183], v[210:213], v[82:85]
	v_mfma_f32_16x16x32_bf16 v[82:85], v[184:187], v[214:217], v[82:85]
	v_mfma_f32_16x16x32_bf16 v[98:101], v[180:183], v[202:205], v[98:101]
	v_mfma_f32_16x16x32_bf16 v[98:101], v[184:187], v[206:209], v[98:101]
	v_mfma_f32_16x16x32_bf16 v[114:117], v[180:183], v[188:191], v[114:117]
	v_mfma_f32_16x16x32_bf16 v[114:117], v[184:187], v[198:201], v[114:117]
	s_setprio 0
	s_barrier
	s_add_u32 s46, s44, 0x8000
	s_addc_u32 s47, s45, 0
	s_add_i32 s70, s70, s3
	s_mov_b32 m0, s70
	ds_read_b128 v[188:191], v155 offset:49152
	ds_read_b128 v[198:201], v155 offset:50176
	ds_read_b128 v[202:205], v155 offset:51200
	ds_read_b128 v[206:209], v155 offset:52224
	ds_read_b128 v[210:213], v155 offset:53248
	ds_read_b128 v[214:217], v155 offset:54272
	ds_read_b128 v[218:221], v155 offset:55296
	ds_read_b128 v[222:225], v155 offset:56320
	global_load_lds_dwordx4 v132, s[46:47]
	s_add_i32 m0, s70, 0x2000
	s_add_u32 s44, s44, 0xc000
	v_lshl_add_u64 v[226:227], s[46:47], 0, v[136:137]
	s_addc_u32 s45, s45, 0
	s_add_i32 s46, s71, s3
	global_load_lds_dwordx4 v[226:227], off
	s_mov_b32 m0, s46
	s_nop 0
	global_load_lds_dwordx4 v132, s[44:45]
	s_add_i32 m0, s46, 0x2000
	s_nop 0
	global_load_lds_dwordx4 v136, s[44:45]
	s_waitcnt vmcnt(6)
	s_waitcnt lgkmcnt(0)
	s_barrier
	s_setprio 1
	s_waitcnt lgkmcnt(0)
	v_mfma_f32_16x16x32_bf16 v[62:65], v[148:151], v[188:191], v[62:65]
	v_mfma_f32_16x16x32_bf16 v[62:65], v[158:161], v[198:201], v[62:65]
	v_mfma_f32_16x16x32_bf16 v[46:49], v[148:151], v[202:205], v[46:49]
	v_mfma_f32_16x16x32_bf16 v[46:49], v[158:161], v[206:209], v[46:49]
	v_mfma_f32_16x16x32_bf16 v[30:33], v[148:151], v[210:213], v[30:33]
	v_mfma_f32_16x16x32_bf16 v[30:33], v[158:161], v[214:217], v[30:33]
	v_mfma_f32_16x16x32_bf16 v[14:17], v[148:151], v[218:221], v[14:17]
	v_mfma_f32_16x16x32_bf16 v[14:17], v[158:161], v[222:225], v[14:17]
	v_mfma_f32_16x16x32_bf16 v[10:13], v[162:165], v[218:221], v[10:13]
	v_mfma_f32_16x16x32_bf16 v[10:13], v[166:169], v[222:225], v[10:13]
	v_mfma_f32_16x16x32_bf16 v[26:29], v[162:165], v[210:213], v[26:29]
	v_mfma_f32_16x16x32_bf16 v[26:29], v[166:169], v[214:217], v[26:29]
	v_mfma_f32_16x16x32_bf16 v[42:45], v[162:165], v[202:205], v[42:45]
	v_mfma_f32_16x16x32_bf16 v[42:45], v[166:169], v[206:209], v[42:45]
	v_mfma_f32_16x16x32_bf16 v[58:61], v[162:165], v[188:191], v[58:61]
	v_mfma_f32_16x16x32_bf16 v[58:61], v[166:169], v[198:201], v[58:61]
	s_setprio 0
	s_setprio 1
	v_mfma_f32_16x16x32_bf16 v[54:57], v[170:173], v[188:191], v[54:57]
	v_mfma_f32_16x16x32_bf16 v[54:57], v[174:177], v[198:201], v[54:57]
	v_mfma_f32_16x16x32_bf16 v[38:41], v[170:173], v[202:205], v[38:41]
	v_mfma_f32_16x16x32_bf16 v[38:41], v[174:177], v[206:209], v[38:41]
	v_mfma_f32_16x16x32_bf16 v[22:25], v[170:173], v[210:213], v[22:25]
	v_mfma_f32_16x16x32_bf16 v[22:25], v[174:177], v[214:217], v[22:25]
	v_mfma_f32_16x16x32_bf16 v[6:9], v[170:173], v[218:221], v[6:9]
	v_mfma_f32_16x16x32_bf16 v[6:9], v[174:177], v[222:225], v[6:9]
	v_mfma_f32_16x16x32_bf16 v[2:5], v[180:183], v[218:221], v[2:5]
	v_mfma_f32_16x16x32_bf16 v[2:5], v[184:187], v[222:225], v[2:5]
	v_mfma_f32_16x16x32_bf16 v[18:21], v[180:183], v[210:213], v[18:21]
	v_mfma_f32_16x16x32_bf16 v[18:21], v[184:187], v[214:217], v[18:21]
	v_mfma_f32_16x16x32_bf16 v[34:37], v[180:183], v[202:205], v[34:37]
	v_mfma_f32_16x16x32_bf16 v[34:37], v[184:187], v[206:209], v[34:37]
	v_mfma_f32_16x16x32_bf16 v[50:53], v[180:183], v[188:191], v[50:53]
	v_mfma_f32_16x16x32_bf16 v[50:53], v[184:187], v[198:201], v[50:53]
	s_setprio 0
	s_barrier
	s_add_i32 s69, s69, 2
	s_add_u32 s40, s40, 0x10000
	s_addc_u32 s41, s41, 0
	s_add_u32 s67, s67, 0x10000
	s_addc_u32 s68, s68, 0
	s_cmp_gt_u32 s69, 61
	s_cbranch_scc0 .LBB0_840
	s_and_b64 vcc, exec, s[14:15]
	s_cbranch_vccz .LBB0_843
	s_barrier

; #define PG8_STAGE(bufoff, gbase, voff) do { _Pragma("unroll") for (int _i = 0; _i < 2; ++_i) \
;         __builtin_amdgcn_global_load_lds((const unsigned*)((const char*)(gbase) + (voff)[_i]), (PG8_LAS unsigned*)(lds + (bufoff) + ldsw + _i * 8192), 16, 0, 0); } while (0)
; #define PG8_LDA(dst, b, h) do { _Pragma("unroll") for (int m = 0; m < 4; ++m) _Pragma("unroll") for (int k = 0; k < 2; ++k) dst[m][k] = *(const PG8_LAS bf16x8*)(lds + PG8_SA(b, h) + aoff + m * 2048 + k * 1024); } while (0)
; #define PG8_LDB(dst, b, h) do { _Pragma("unroll") for (int n = 0; n < 2; ++n) _Pragma("unroll") for (int k = 0; k < 2; ++k) dst[n][k] = *(const PG8_LAS bf16x8*)(lds + PG8_SB(b, h) + boff + n * 2048 + k * 1024); } while (0)
; #define PG8_MMA(ai, bj, At, Bt) do { __builtin_amdgcn_s_setprio(1); _Pragma("unroll") for (int m = 0; m < 4; ++m) _Pragma("unroll") for (int n = 0; n < 2; ++n) _Pragma("unroll") for (int k = 0; k < 2; ++k) \
;         acc[ai][bj][m][n] = __builtin_amdgcn_mfma_f32_16x16x32_bf16(Bt[n][k], At[m][k], acc[ai][bj][m][n], 0, 0, 0); __builtin_amdgcn_s_setprio(0); } while (0)
; #define PG8_WAIT_V(n) asm volatile("s_waitcnt vmcnt(" #n ")" ::: "memory")
; #define PG8_WAIT_L(n) asm volatile("s_waitcnt lgkmcnt(" #n ")" ::: "memory")
; template <class Epi, class Sched, bool ALIGN_EPI = false, bool SP2 = false>
; __device__ __forceinline__ void gemm_phase(PG8_LAS unsigned char* lds, const Gemm g, const Sched& S, const Epi& E) {
;     ...
;             const bool last = (t == nt - 2);
;             const char* a1 = cA + (size_t)(t + 1) * kstep;
;             const char* a2 = last ? nA : cA + (size_t)(t + 2) * kstep; const char* b2 = last ? nB : cB + (size_t)(t + 2) * kstep;
;             const char* a3 = a2 + kstep; const char* b3 = b2 + kstep;
;             if (last && has_next) S.a_ready(nxt);
;             if constexpr (SP2) {
;             PG8_LDB(B0, 0, 0); PG8_LDB(B1, 0, 1); PG8_SCHED; PG8_LDA(At, 0, 0); PG8_STAGE(PG8_SA(1, 1), a1 + hstep, voffA);
;             PG8_WAIT_V(8); PG8_WAIT_L(0); PG8_BAR; PG8_MMA(0, 0, At, B0); PG8_MMA(0, 1, At, B1); PG8_BAR; PG8_SCHED;
;             PG8_LDA(At, 0, 1); PG8_STAGE(PG8_SB(0, 0), b2, voffB); PG8_STAGE(PG8_SB(0, 1), b2 + hstep, voffB); PG8_STAGE(PG8_SA(0, 0), a2, voffA);
;             PG8_WAIT_V(8); PG8_WAIT_L(0); PG8_BAR; PG8_MMA(1, 0, At, B0); PG8_MMA(1, 1, At, B1); PG8_BAR; PG8_SCHED;
.LBB0_939:
	s_or_b32 s24, s59, 1
	s_lshl_b64 s[62:63], s[24:25], 15
	s_add_i32 s24, s59, 2
	ds_read_b128 v[156:159], v193
	ds_read_b128 v[160:163], v193 offset:1024
	ds_read_b128 v[196:199], v193 offset:2048
	ds_read_b128 v[200:203], v193 offset:3072
	ds_read_b128 v[204:207], v194
	ds_read_b128 v[208:211], v194 offset:1024
	ds_read_b128 v[212:215], v194 offset:2048
	ds_read_b128 v[216:219], v194 offset:3072
	s_lshl_b64 s[8:9], s[24:25], 15
	s_add_u32 s44, s6, s8
	s_addc_u32 s45, s7, s9
	s_cmpk_eq_i32 s59, 0xaa
	s_cselect_b32 s46, s58, s44
	s_cselect_b32 s47, s56, s45
	s_cselect_b32 s44, 0, s8
	s_cselect_b32 s45, 0, s9
	s_add_u32 s8, s46, 0x8000
	s_addc_u32 s9, s47, 0
	s_add_u32 s44, s14, s44
	s_addc_u32 s45, s15, s45
	s_add_u32 s62, s6, s62
	s_addc_u32 s63, s7, s63
	s_add_u32 s62, s62, 0x4000
	s_addc_u32 s63, s63, 0
	s_sub_u32 s8, s62, 0x4000
	s_subb_u32 s9, s63, 0
	s_mov_b32 m0, s51
	s_nop 0
	global_load_lds_dwordx4 v130, s[8:9]
	s_mov_b32 m0, s57
	s_nop 0
	global_load_lds_dwordx4 v134, s[8:9]
	s_add_i32 m0, s30, 0xc000
	ds_read_b128 v[220:223], v186
	ds_read_b128 v[224:227], v186 offset:1024
	ds_read_b128 v[228:231], v186 offset:2048
	ds_read_b128 v[232:235], v186 offset:3072
	ds_read_b128 v[236:239], v186 offset:4096
	ds_read_b128 v[240:243], v186 offset:5120
	ds_read_b128 v[244:247], v186 offset:6144
	ds_read_b128 v[248:251], v186 offset:7168
	global_load_lds_dwordx4 v130, s[62:63]
	s_add_i32 m0, s30, 0xe000
	s_nop 0
	global_load_lds_dwordx4 v134, s[62:63]
	s_waitcnt vmcnt(8)
	s_waitcnt lgkmcnt(0)
	s_barrier
	s_setprio 1
	s_waitcnt lgkmcnt(0)
	v_mfma_f32_16x16x32_bf16 v[126:129], v[156:159], v[220:223], v[126:129]
	v_mfma_f32_16x16x32_bf16 v[126:129], v[160:163], v[224:227], v[126:129]
	v_mfma_f32_16x16x32_bf16 v[110:113], v[156:159], v[228:231], v[110:113]
	v_mfma_f32_16x16x32_bf16 v[110:113], v[160:163], v[232:235], v[110:113]
	v_mfma_f32_16x16x32_bf16 v[94:97], v[156:159], v[236:239], v[94:97]
	v_mfma_f32_16x16x32_bf16 v[94:97], v[160:163], v[240:243], v[94:97]
	v_mfma_f32_16x16x32_bf16 v[78:81], v[156:159], v[244:247], v[78:81]
	v_mfma_f32_16x16x32_bf16 v[78:81], v[160:163], v[248:251], v[78:81]
	v_mfma_f32_16x16x32_bf16 v[74:77], v[196:199], v[244:247], v[74:77]
	v_mfma_f32_16x16x32_bf16 v[74:77], v[200:203], v[248:251], v[74:77]
	v_mfma_f32_16x16x32_bf16 v[90:93], v[196:199], v[236:239], v[90:93]
	v_mfma_f32_16x16x32_bf16 v[90:93], v[200:203], v[240:243], v[90:93]
	v_mfma_f32_16x16x32_bf16 v[106:109], v[196:199], v[228:231], v[106:109]
	v_mfma_f32_16x16x32_bf16 v[106:109], v[200:203], v[232:235], v[106:109]
	v_mfma_f32_16x16x32_bf16 v[122:125], v[196:199], v[220:223], v[122:125]
	v_mfma_f32_16x16x32_bf16 v[122:125], v[200:203], v[224:227], v[122:125]
	s_setprio 0
	s_setprio 1
	v_mfma_f32_16x16x32_bf16 v[118:121], v[204:207], v[220:223], v[118:121]
	v_mfma_f32_16x16x32_bf16 v[118:121], v[208:211], v[224:227], v[118:121]
	v_mfma_f32_16x16x32_bf16 v[102:105], v[204:207], v[228:231], v[102:105]
	v_mfma_f32_16x16x32_bf16 v[102:105], v[208:211], v[232:235], v[102:105]
	v_mfma_f32_16x16x32_bf16 v[86:89], v[204:207], v[236:239], v[86:89]
	v_mfma_f32_16x16x32_bf16 v[86:89], v[208:211], v[240:243], v[86:89]
	v_mfma_f32_16x16x32_bf16 v[70:73], v[204:207], v[244:247], v[70:73]
	v_mfma_f32_16x16x32_bf16 v[70:73], v[208:211], v[248:251], v[70:73]
	v_mfma_f32_16x16x32_bf16 v[66:69], v[212:215], v[244:247], v[66:69]
	v_mfma_f32_16x16x32_bf16 v[66:69], v[216:219], v[248:251], v[66:69]
	v_mfma_f32_16x16x32_bf16 v[82:85], v[212:215], v[236:239], v[82:85]
	v_mfma_f32_16x16x32_bf16 v[82:85], v[216:219], v[240:243], v[82:85]
	v_mfma_f32_16x16x32_bf16 v[98:101], v[212:215], v[228:231], v[98:101]
	v_mfma_f32_16x16x32_bf16 v[98:101], v[216:219], v[232:235], v[98:101]
	v_mfma_f32_16x16x32_bf16 v[114:117], v[212:215], v[220:223], v[114:117]
	v_mfma_f32_16x16x32_bf16 v[114:117], v[216:219], v[224:227], v[114:117]
	s_setprio 0
	s_barrier
	s_add_i32 s62, s67, s29
	s_mov_b32 m0, s62
	ds_read_b128 v[220:223], v186 offset:16384
	ds_read_b128 v[224:227], v186 offset:17408
	ds_read_b128 v[228:231], v186 offset:18432
	ds_read_b128 v[232:235], v186 offset:19456
	ds_read_b128 v[236:239], v186 offset:20480
	ds_read_b128 v[240:243], v186 offset:21504
	ds_read_b128 v[244:247], v186 offset:22528
	ds_read_b128 v[248:251], v186 offset:23552
	global_load_lds_dwordx4 v132, s[44:45]
	s_add_i32 m0, s62, 0x2000
	s_add_u32 s62, s44, 0x4000
	v_lshl_add_u64 v[164:165], s[44:45], 0, v[136:137]
	s_addc_u32 s63, s45, 0
	s_add_i32 s72, s68, s29
	global_load_lds_dwordx4 v[164:165], off
	s_mov_b32 m0, s72
	s_nop 0
	global_load_lds_dwordx4 v132, s[62:63]
	s_add_i32 m0, s72, 0x2000
	s_nop 0
	global_load_lds_dwordx4 v136, s[62:63]
	s_waitcnt vmcnt(6)
	s_waitcnt lgkmcnt(0)
	s_barrier
; #define PG8_STAGE(bufoff, gbase, voff) do { _Pragma("unroll") for (int _i = 0; _i < 2; ++_i) \
;         __builtin_amdgcn_global_load_lds((const unsigned*)((const char*)(gbase) + (voff)[_i]), (PG8_LAS unsigned*)(lds + (bufoff) + ldsw + _i * 8192), 16, 0, 0); } while (0)
; #define PG8_LDA(dst, b, h) do { _Pragma("unroll") for (int m = 0; m < 4; ++m) _Pragma("unroll") for (int k = 0; k < 2; ++k) dst[m][k] = *(const PG8_LAS bf16x8*)(lds + PG8_SA(b, h) + aoff + m * 2048 + k * 1024); } while (0)
; #define PG8_LDB(dst, b, h) do { _Pragma("unroll") for (int n = 0; n < 2; ++n) _Pragma("unroll") for (int k = 0; k < 2; ++k) dst[n][k] = *(const PG8_LAS bf16x8*)(lds + PG8_SB(b, h) + boff + n * 2048 + k * 1024); } while (0)
; #define PG8_MMA(ai, bj, At, Bt) do { __builtin_amdgcn_s_setprio(1); _Pragma("unroll") for (int m = 0; m < 4; ++m) _Pragma("unroll") for (int n = 0; n < 2; ++n) _Pragma("unroll") for (int k = 0; k < 2; ++k) \
;         acc[ai][bj][m][n] = __builtin_amdgcn_mfma_f32_16x16x32_bf16(Bt[n][k], At[m][k], acc[ai][bj][m][n], 0, 0, 0); __builtin_amdgcn_s_setprio(0); } while (0)
; #define PG8_WAIT_V(n) asm volatile("s_waitcnt vmcnt(" #n ")" ::: "memory")
; #define PG8_WAIT_L(n) asm volatile("s_waitcnt lgkmcnt(" #n ")" ::: "memory")
; #define PG8_BAR __builtin_amdgcn_s_barrier()
; #define PG8_SCHED __builtin_amdgcn_sched_barrier(0)
; template <class Epi, class Sched, bool ALIGN_EPI = false, bool SP2 = false>
; __device__ __forceinline__ void gemm_phase(PG8_LAS unsigned char* lds, const Gemm g, const Sched& S, const Epi& E) {
;     ...
;             PG8_WAIT_V(8); PG8_WAIT_L(0); PG8_BAR; PG8_MMA(0, 0, At, B0); PG8_MMA(0, 1, At, B1); PG8_BAR; PG8_SCHED;
;             PG8_LDA(At, 0, 1); PG8_STAGE(PG8_SB(0, 0), b2, voffB); PG8_STAGE(PG8_SB(0, 1), b2 + hstep, voffB); PG8_STAGE(PG8_SA(0, 0), a2, voffA);
;             PG8_WAIT_V(8); PG8_WAIT_L(0); PG8_BAR; PG8_MMA(1, 0, At, B0); PG8_MMA(1, 1, At, B1); PG8_BAR; PG8_SCHED;
;             PG8_LDB(B0, 1, 0); PG8_LDB(B1, 1, 1); PG8_SCHED; PG8_LDA(At, 1, 0); PG8_STAGE(PG8_SA(0, 1), a2 + hstep, voffA);
;             PG8_WAIT_V(8); PG8_WAIT_L(0); PG8_BAR; PG8_MMA(0, 0, At, B0); PG8_MMA(0, 1, At, B1); PG8_BAR; PG8_SCHED;
	s_setprio 1
	s_waitcnt lgkmcnt(0)
	v_mfma_f32_16x16x32_bf16 v[62:65], v[156:159], v[220:223], v[62:65]
	v_mfma_f32_16x16x32_bf16 v[62:65], v[160:163], v[224:227], v[62:65]
	v_mfma_f32_16x16x32_bf16 v[46:49], v[156:159], v[228:231], v[46:49]
	v_mfma_f32_16x16x32_bf16 v[46:49], v[160:163], v[232:235], v[46:49]
	v_mfma_f32_16x16x32_bf16 v[30:33], v[156:159], v[236:239], v[30:33]
	v_mfma_f32_16x16x32_bf16 v[30:33], v[160:163], v[240:243], v[30:33]
	v_mfma_f32_16x16x32_bf16 v[14:17], v[156:159], v[244:247], v[14:17]
	v_mfma_f32_16x16x32_bf16 v[14:17], v[160:163], v[248:251], v[14:17]
	v_mfma_f32_16x16x32_bf16 v[10:13], v[196:199], v[244:247], v[10:13]
	v_mfma_f32_16x16x32_bf16 v[10:13], v[200:203], v[248:251], v[10:13]
	v_mfma_f32_16x16x32_bf16 v[26:29], v[196:199], v[236:239], v[26:29]
	v_mfma_f32_16x16x32_bf16 v[26:29], v[200:203], v[240:243], v[26:29]
	v_mfma_f32_16x16x32_bf16 v[42:45], v[196:199], v[228:231], v[42:45]
	v_mfma_f32_16x16x32_bf16 v[42:45], v[200:203], v[232:235], v[42:45]
	v_mfma_f32_16x16x32_bf16 v[58:61], v[196:199], v[220:223], v[58:61]
	v_mfma_f32_16x16x32_bf16 v[58:61], v[200:203], v[224:227], v[58:61]
	s_setprio 0
	s_setprio 1
	v_mfma_f32_16x16x32_bf16 v[54:57], v[204:207], v[220:223], v[54:57]
	v_mfma_f32_16x16x32_bf16 v[54:57], v[208:211], v[224:227], v[54:57]
	v_mfma_f32_16x16x32_bf16 v[38:41], v[204:207], v[228:231], v[38:41]
	v_mfma_f32_16x16x32_bf16 v[38:41], v[208:211], v[232:235], v[38:41]
	v_mfma_f32_16x16x32_bf16 v[22:25], v[204:207], v[236:239], v[22:25]
	v_mfma_f32_16x16x32_bf16 v[22:25], v[208:211], v[240:243], v[22:25]
	v_mfma_f32_16x16x32_bf16 v[6:9], v[204:207], v[244:247], v[6:9]
	v_mfma_f32_16x16x32_bf16 v[6:9], v[208:211], v[248:251], v[6:9]
	v_mfma_f32_16x16x32_bf16 v[2:5], v[212:215], v[244:247], v[2:5]
	v_mfma_f32_16x16x32_bf16 v[2:5], v[216:219], v[248:251], v[2:5]
	v_mfma_f32_16x16x32_bf16 v[18:21], v[212:215], v[236:239], v[18:21]
	v_mfma_f32_16x16x32_bf16 v[18:21], v[216:219], v[240:243], v[18:21]
	v_mfma_f32_16x16x32_bf16 v[34:37], v[212:215], v[228:231], v[34:37]
	v_mfma_f32_16x16x32_bf16 v[34:37], v[216:219], v[232:235], v[34:37]
	v_mfma_f32_16x16x32_bf16 v[50:53], v[212:215], v[220:223], v[50:53]
	v_mfma_f32_16x16x32_bf16 v[50:53], v[216:219], v[224:227], v[50:53]
	s_setprio 0
	s_barrier
	s_add_i32 s62, 0, 0x18000
	v_add_u32_e32 v145, s62, v166
	s_add_i32 s63, 0, 0x1c000
	ds_read_b128 v[156:159], v145
	ds_read_b128 v[160:163], v145 offset:1024
	ds_read_b128 v[196:199], v145 offset:2048
	ds_read_b128 v[200:203], v145 offset:3072
	v_add_u32_e32 v145, s63, v166
	ds_read_b128 v[204:207], v145
	ds_read_b128 v[208:211], v145 offset:1024
	ds_read_b128 v[212:215], v145 offset:2048
	ds_read_b128 v[216:219], v145 offset:3072
	s_mov_b32 m0, s30
	s_nop 0
	global_load_lds_dwordx4 v130, s[46:47]
	s_mov_b32 m0, s31
	s_nop 0
	global_load_lds_dwordx4 v134, s[46:47]
	s_add_u32 s46, s46, 0x4000
	s_addc_u32 s47, s47, 0
	s_mov_b32 m0, s35
	ds_read_b128 v[220:223], v186 offset:32768
	ds_read_b128 v[224:227], v186 offset:33792
	ds_read_b128 v[228:231], v186 offset:34816
	ds_read_b128 v[232:235], v186 offset:35840
	ds_read_b128 v[236:239], v186 offset:36864
	ds_read_b128 v[240:243], v186 offset:37888
	ds_read_b128 v[244:247], v186 offset:38912
	ds_read_b128 v[248:251], v186 offset:39936
	global_load_lds_dwordx4 v130, s[46:47]
	s_mov_b32 m0, s48
	s_nop 0
	global_load_lds_dwordx4 v134, s[46:47]
	s_waitcnt vmcnt(8)
	s_waitcnt lgkmcnt(0)
	s_barrier
; #define PG8_STAGE(bufoff, gbase, voff) do { _Pragma("unroll") for (int _i = 0; _i < 2; ++_i) \
;         __builtin_amdgcn_global_load_lds((const unsigned*)((const char*)(gbase) + (voff)[_i]), (PG8_LAS unsigned*)(lds + (bufoff) + ldsw + _i * 8192), 16, 0, 0); } while (0)
; #define PG8_LDA(dst, b, h) do { _Pragma("unroll") for (int m = 0; m < 4; ++m) _Pragma("unroll") for (int k = 0; k < 2; ++k) dst[m][k] = *(const PG8_LAS bf16x8*)(lds + PG8_SA(b, h) + aoff + m * 2048 + k * 1024); } while (0)
; #define PG8_MMA(ai, bj, At, Bt) do { __builtin_amdgcn_s_setprio(1); _Pragma("unroll") for (int m = 0; m < 4; ++m) _Pragma("unroll") for (int n = 0; n < 2; ++n) _Pragma("unroll") for (int k = 0; k < 2; ++k) \
;         acc[ai][bj][m][n] = __builtin_amdgcn_mfma_f32_16x16x32_bf16(Bt[n][k], At[m][k], acc[ai][bj][m][n], 0, 0, 0); __builtin_amdgcn_s_setprio(0); } while (0)
; #define PG8_WAIT_V(n) asm volatile("s_waitcnt vmcnt(" #n ")" ::: "memory")
; #define PG8_WAIT_L(n) asm volatile("s_waitcnt lgkmcnt(" #n ")" ::: "memory")
; #define PG8_BAR __builtin_amdgcn_s_barrier()
; #define PG8_SCHED __builtin_amdgcn_sched_barrier(0)
; template <class Epi, class Sched, bool ALIGN_EPI = false, bool SP2 = false>
; __device__ __forceinline__ void gemm_phase(PG8_LAS unsigned char* lds, const Gemm g, const Sched& S, const Epi& E) {
;     ...
;             PG8_WAIT_V(8); PG8_WAIT_L(0); PG8_BAR; PG8_MMA(0, 0, At, B0); PG8_MMA(0, 1, At, B1); PG8_BAR; PG8_SCHED;
;             PG8_LDA(At, 1, 1); PG8_STAGE(PG8_SB(1, 0), b3, voffB); PG8_STAGE(PG8_SB(1, 1), b3 + hstep, voffB); PG8_STAGE(PG8_SA(1, 0), a3, voffA);
;             PG8_WAIT_V(8); PG8_WAIT_L(0); PG8_BAR; PG8_MMA(1, 0, At, B0); PG8_MMA(1, 1, At, B1); PG8_BAR; PG8_SCHED;
	s_setprio 1
	s_waitcnt lgkmcnt(0)
	v_mfma_f32_16x16x32_bf16 v[126:129], v[156:159], v[220:223], v[126:129]
	v_mfma_f32_16x16x32_bf16 v[126:129], v[160:163], v[224:227], v[126:129]
	v_mfma_f32_16x16x32_bf16 v[110:113], v[156:159], v[228:231], v[110:113]
	v_mfma_f32_16x16x32_bf16 v[110:113], v[160:163], v[232:235], v[110:113]
	v_mfma_f32_16x16x32_bf16 v[94:97], v[156:159], v[236:239], v[94:97]
	v_mfma_f32_16x16x32_bf16 v[94:97], v[160:163], v[240:243], v[94:97]
	v_mfma_f32_16x16x32_bf16 v[78:81], v[156:159], v[244:247], v[78:81]
	v_mfma_f32_16x16x32_bf16 v[78:81], v[160:163], v[248:251], v[78:81]
	v_mfma_f32_16x16x32_bf16 v[74:77], v[196:199], v[244:247], v[74:77]
	v_mfma_f32_16x16x32_bf16 v[74:77], v[200:203], v[248:251], v[74:77]
	v_mfma_f32_16x16x32_bf16 v[90:93], v[196:199], v[236:239], v[90:93]
	v_mfma_f32_16x16x32_bf16 v[90:93], v[200:203], v[240:243], v[90:93]
	v_mfma_f32_16x16x32_bf16 v[106:109], v[196:199], v[228:231], v[106:109]
	v_mfma_f32_16x16x32_bf16 v[106:109], v[200:203], v[232:235], v[106:109]
	v_mfma_f32_16x16x32_bf16 v[122:125], v[196:199], v[220:223], v[122:125]
	v_mfma_f32_16x16x32_bf16 v[122:125], v[200:203], v[224:227], v[122:125]
	s_setprio 0
	s_setprio 1
	v_mfma_f32_16x16x32_bf16 v[118:121], v[204:207], v[220:223], v[118:121]
	v_mfma_f32_16x16x32_bf16 v[118:121], v[208:211], v[224:227], v[118:121]
	v_mfma_f32_16x16x32_bf16 v[102:105], v[204:207], v[228:231], v[102:105]
	v_mfma_f32_16x16x32_bf16 v[102:105], v[208:211], v[232:235], v[102:105]
	v_mfma_f32_16x16x32_bf16 v[86:89], v[204:207], v[236:239], v[86:89]
	v_mfma_f32_16x16x32_bf16 v[86:89], v[208:211], v[240:243], v[86:89]
	v_mfma_f32_16x16x32_bf16 v[70:73], v[204:207], v[244:247], v[70:73]
	v_mfma_f32_16x16x32_bf16 v[70:73], v[208:211], v[248:251], v[70:73]
	v_mfma_f32_16x16x32_bf16 v[66:69], v[212:215], v[244:247], v[66:69]
	v_mfma_f32_16x16x32_bf16 v[66:69], v[216:219], v[248:251], v[66:69]
	v_mfma_f32_16x16x32_bf16 v[82:85], v[212:215], v[236:239], v[82:85]
	v_mfma_f32_16x16x32_bf16 v[82:85], v[216:219], v[240:243], v[82:85]
	v_mfma_f32_16x16x32_bf16 v[98:101], v[212:215], v[228:231], v[98:101]
	v_mfma_f32_16x16x32_bf16 v[98:101], v[216:219], v[232:235], v[98:101]
	v_mfma_f32_16x16x32_bf16 v[114:117], v[212:215], v[220:223], v[114:117]
	v_mfma_f32_16x16x32_bf16 v[114:117], v[216:219], v[224:227], v[114:117]
	s_setprio 0
	s_barrier
	s_add_u32 s46, s44, 0x8000
	s_addc_u32 s47, s45, 0
	s_add_i32 s62, s62, s29
	s_mov_b32 m0, s62
	ds_read_b128 v[220:223], v186 offset:49152
	ds_read_b128 v[224:227], v186 offset:50176
	ds_read_b128 v[228:231], v186 offset:51200
	ds_read_b128 v[232:235], v186 offset:52224
	ds_read_b128 v[236:239], v186 offset:53248
	ds_read_b128 v[240:243], v186 offset:54272
	ds_read_b128 v[244:247], v186 offset:55296
	ds_read_b128 v[248:251], v186 offset:56320
	global_load_lds_dwordx4 v132, s[46:47]
	s_add_i32 m0, s62, 0x2000
	s_add_u32 s44, s44, 0xc000
	v_lshl_add_u64 v[164:165], s[46:47], 0, v[136:137]
	s_addc_u32 s45, s45, 0
	s_add_i32 s46, s63, s29
	global_load_lds_dwordx4 v[164:165], off
	s_mov_b32 m0, s46
	s_nop 0
	global_load_lds_dwordx4 v132, s[44:45]
	s_add_i32 m0, s46, 0x2000
	s_nop 0
	global_load_lds_dwordx4 v136, s[44:45]
	s_waitcnt vmcnt(6)
	s_waitcnt lgkmcnt(0)
	s_barrier
	s_setprio 1
	s_waitcnt lgkmcnt(0)
	v_mfma_f32_16x16x32_bf16 v[62:65], v[156:159], v[220:223], v[62:65]
	v_mfma_f32_16x16x32_bf16 v[62:65], v[160:163], v[224:227], v[62:65]
	v_mfma_f32_16x16x32_bf16 v[46:49], v[156:159], v[228:231], v[46:49]
	v_mfma_f32_16x16x32_bf16 v[46:49], v[160:163], v[232:235], v[46:49]
	v_mfma_f32_16x16x32_bf16 v[30:33], v[156:159], v[236:239], v[30:33]
	v_mfma_f32_16x16x32_bf16 v[30:33], v[160:163], v[240:243], v[30:33]
	v_mfma_f32_16x16x32_bf16 v[14:17], v[156:159], v[244:247], v[14:17]
	v_mfma_f32_16x16x32_bf16 v[14:17], v[160:163], v[248:251], v[14:17]
	v_mfma_f32_16x16x32_bf16 v[10:13], v[196:199], v[244:247], v[10:13]
	v_mfma_f32_16x16x32_bf16 v[10:13], v[200:203], v[248:251], v[10:13]
	v_mfma_f32_16x16x32_bf16 v[26:29], v[196:199], v[236:239], v[26:29]
	v_mfma_f32_16x16x32_bf16 v[26:29], v[200:203], v[240:243], v[26:29]
	v_mfma_f32_16x16x32_bf16 v[42:45], v[196:199], v[228:231], v[42:45]
	v_mfma_f32_16x16x32_bf16 v[42:45], v[200:203], v[232:235], v[42:45]
	v_mfma_f32_16x16x32_bf16 v[58:61], v[196:199], v[220:223], v[58:61]
	v_mfma_f32_16x16x32_bf16 v[58:61], v[200:203], v[224:227], v[58:61]
	s_setprio 0
	s_setprio 1
	v_mfma_f32_16x16x32_bf16 v[54:57], v[204:207], v[220:223], v[54:57]
	v_mfma_f32_16x16x32_bf16 v[54:57], v[208:211], v[224:227], v[54:57]
	v_mfma_f32_16x16x32_bf16 v[38:41], v[204:207], v[228:231], v[38:41]
	v_mfma_f32_16x16x32_bf16 v[38:41], v[208:211], v[232:235], v[38:41]
	v_mfma_f32_16x16x32_bf16 v[22:25], v[204:207], v[236:239], v[22:25]
	v_mfma_f32_16x16x32_bf16 v[22:25], v[208:211], v[240:243], v[22:25]
	v_mfma_f32_16x16x32_bf16 v[6:9], v[204:207], v[244:247], v[6:9]
	v_mfma_f32_16x16x32_bf16 v[6:9], v[208:211], v[248:251], v[6:9]
	v_mfma_f32_16x16x32_bf16 v[2:5], v[212:215], v[244:247], v[2:5]
	v_mfma_f32_16x16x32_bf16 v[2:5], v[216:219], v[248:251], v[2:5]
	v_mfma_f32_16x16x32_bf16 v[18:21], v[212:215], v[236:239], v[18:21]
	v_mfma_f32_16x16x32_bf16 v[18:21], v[216:219], v[240:243], v[18:21]
	v_mfma_f32_16x16x32_bf16 v[34:37], v[212:215], v[228:231], v[34:37]
	v_mfma_f32_16x16x32_bf16 v[34:37], v[216:219], v[232:235], v[34:37]
	v_mfma_f32_16x16x32_bf16 v[50:53], v[212:215], v[220:223], v[50:53]
	v_mfma_f32_16x16x32_bf16 v[50:53], v[216:219], v[224:227], v[50:53]
	s_setprio 0
	s_barrier
	s_cmpk_gt_u32 s59, 0xa9
	s_mov_b32 s59, s24
	s_cbranch_scc0 .LBB0_939
	s_and_b64 vcc, exec, s[38:39]
	s_cbranch_vccz .LBB0_942
	s_barrier
